# all-global memory ops; batched the serialized global loads in the hyena gate prologue/epilogue, the filter-MLP hidden jobs and the modulation GEMV k-loop (same arithmetic order)
# speedup vs baseline: 1.0385x; 1.0385x over previous
; __device__ __forceinline__ void p0_job(const Params& p, char* smem, int job) {
;     ...
;     for (int step = 0; step < 8; ++step) {
;       int t = tch * 32 + step * 4 + tg;
;       if (j < 33) {
;         float z;
;         if (j == 0) z = (float)t / (float)(L - 1);
;         else {
;           int bnd = (j - 1) & 15;
;           float f = 1e-4f + (float)bnd * ((15.0f - 1e-4f) / 15.0f);
;           float w = wstep * (float)t;
;           z = (j <= 16) ? cosf(f * w) : -sinf(f * w);
;         }
;         zf[tg * 36 + j] = z;
;       }
;       __syncthreads();
;       float a = b1;
;       for (int i = 0; i < 33; ++i) a += zf[tg * 36 + i] * w1[i * 64 + j];
;       h1s[tg * 64 + j] = sinf(fr * a);
.LBB0_54:
	s_or_b64 exec, exec, s[26:27]
	s_waitcnt lgkmcnt(0)
	s_barrier
	ds_read_b128 v[0:3], v166
	ds_read_b128 v[174:177], v166 offset:16
	ds_read_b128 v[178:181], v166 offset:32
	ds_read_b128 v[182:185], v166 offset:48
	global_load_dword v240, v[10:11], off
	global_load_dword v241, v[12:13], off
	global_load_dword v242, v[10:11], off offset:256
	global_load_dword v243, v[10:11], off offset:512
	global_load_dword v244, v[10:11], off offset:768
	global_load_dword v245, v[10:11], off offset:1024
	global_load_dword v246, v[10:11], off offset:1280
	global_load_dword v247, v[10:11], off offset:1536
	global_load_dword v248, v[10:11], off offset:1792
	global_load_dword v249, v[10:11], off offset:2048
	global_load_dword v250, v[10:11], off offset:2304
	global_load_dword v251, v[10:11], off offset:2560
	global_load_dword v252, v[10:11], off offset:2816
	global_load_dword v253, v[10:11], off offset:3072
	global_load_dword v254, v[10:11], off offset:3328
	global_load_dword v255, v[10:11], off offset:3584
	s_waitcnt vmcnt(0)
	s_waitcnt lgkmcnt(0)
	v_fma_f32 v4, v0, v240, v162
	v_fmac_f32_e32 v4, v1, v242
	v_fmac_f32_e32 v4, v2, v243
	v_fmac_f32_e32 v4, v3, v244
	v_fmac_f32_e32 v4, v174, v245
	v_fmac_f32_e32 v4, v175, v246
	v_fmac_f32_e32 v4, v176, v247
	v_fmac_f32_e32 v4, v177, v248
	v_fmac_f32_e32 v4, v178, v249
	v_fmac_f32_e32 v4, v179, v250
	v_fmac_f32_e32 v4, v180, v251
	v_fmac_f32_e32 v4, v181, v252
	v_fmac_f32_e32 v4, v182, v253
	v_fmac_f32_e32 v4, v183, v254
	v_fmac_f32_e32 v4, v184, v255
	global_load_dword v240, v[10:11], off offset:3840
	global_load_dword v242, v[14:15], off
	global_load_dword v243, v[16:17], off
	global_load_dword v244, v[18:19], off
	global_load_dword v245, v[20:21], off
	global_load_dword v246, v[22:23], off
	global_load_dword v247, v[24:25], off
	global_load_dword v248, v[26:27], off
	global_load_dword v249, v[28:29], off
	global_load_dword v250, v[30:31], off
	global_load_dword v251, v[32:33], off
	global_load_dword v252, v[34:35], off
	global_load_dword v253, v[36:37], off
	s_waitcnt vmcnt(0)
	v_fmac_f32_e32 v4, v185, v240
	ds_read_b128 v[0:3], v166 offset:64
	s_waitcnt lgkmcnt(0)
	v_fmac_f32_e32 v4, v0, v241
	v_fmac_f32_e32 v4, v1, v242
	v_fmac_f32_e32 v4, v2, v243
	v_fmac_f32_e32 v4, v3, v244
	ds_read_b96 v[0:2], v166 offset:80
	s_waitcnt lgkmcnt(0)
	v_fmac_f32_e32 v4, v0, v245
	v_fmac_f32_e32 v4, v1, v246
	v_fmac_f32_e32 v4, v2, v247
	ds_read2_b32 v[2:3], v166 offset0:23 offset1:24
	s_waitcnt lgkmcnt(0)
	v_pk_mul_f32 v[0:1], v[2:3], v[248:249]
	s_nop 0
	v_add_f32_e32 v0, v4, v0
	v_add_f32_e32 v4, v0, v1
	ds_read2_b32 v[2:3], v166 offset0:25 offset1:26
	s_waitcnt lgkmcnt(0)
	v_pk_mul_f32 v[0:1], v[2:3], v[250:251]
	s_nop 0
	v_add_f32_e32 v0, v4, v0
	v_add_f32_e32 v4, v0, v1
	ds_read2_b32 v[2:3], v166 offset0:27 offset1:28
	s_waitcnt lgkmcnt(0)
	v_pk_mul_f32 v[0:1], v[2:3], v[252:253]
	s_nop 0
	v_add_f32_e32 v0, v4, v0
	v_add_f32_e32 v4, v0, v1
	global_load_dword v242, v[38:39], off
	global_load_dword v243, v[40:41], off
	global_load_dword v244, v[42:43], off
	global_load_dword v245, v[44:45], off
	s_waitcnt vmcnt(0)
	ds_read2_b32 v[2:3], v166 offset0:29 offset1:30
	s_waitcnt lgkmcnt(0)
	v_pk_mul_f32 v[0:1], v[2:3], v[242:243]
	s_nop 0
	v_add_f32_e32 v0, v4, v0
	v_add_f32_e32 v4, v0, v1
	ds_read2_b32 v[2:3], v166 offset0:31 offset1:32
	s_waitcnt lgkmcnt(0)
	v_pk_mul_f32 v[0:1], v[2:3], v[244:245]
	s_nop 0
	v_add_f32_e32 v0, v4, v0
	v_add_f32_e32 v0, v0, v1
	v_mul_f32_e32 v0, v164, v0
	v_and_b32_e32 v1, 0x7fffffff, v0
	v_cmp_nlt_f32_e64 s[0:1], |v0|, s47
	s_and_saveexec_b64 s[10:11], s[0:1]
	s_xor_b64 s[26:27], exec, s[10:11]
	s_cbranch_execz .LBB0_56
	v_lshrrev_b32_e32 v2, 23, v1
	v_add_u32_e32 v2, 0xffffff88, v2
	v_cmp_lt_u32_e32 vcc, 63, v2
	s_nop 1
	v_cndmask_b32_e32 v3, 0, v156, vcc
	v_add_u32_e32 v2, v3, v2
	v_cmp_lt_u32_e64 s[0:1], 31, v2
	s_nop 1
	v_cndmask_b32_e64 v3, 0, v157, s[0:1]
	v_add_u32_e32 v2, v3, v2
	v_cmp_lt_u32_e64 s[12:13], 31, v2
	s_nop 1
	v_cndmask_b32_e64 v3, 0, v157, s[12:13]
	v_add_u32_e32 v147, v3, v2
	v_and_b32_e32 v2, 0x7fffff, v1
	v_or_b32_e32 v173, 0x800000, v2
	v_mad_u64_u32 v[2:3], s[10:11], v173, s48, 0
	v_mov_b32_e32 v4, v3
	v_mad_u64_u32 v[170:171], s[10:11], v173, s49, v[4:5]
	v_mov_b32_e32 v4, v171
	v_mad_u64_u32 v[174:175], s[10:11], v173, s50, v[4:5]
	v_mov_b32_e32 v4, v175
	v_mad_u64_u32 v[176:177], s[10:11], v173, s51, v[4:5]
	v_mov_b32_e32 v4, v177
	v_mad_u64_u32 v[178:179], s[10:11], v173, s52, v[4:5]
	v_mov_b32_e32 v4, v179
	v_mad_u64_u32 v[180:181], s[10:11], v173, s53, v[4:5]
	v_mov_b32_e32 v4, v181
	v_mad_u64_u32 v[182:183], s[10:11], v173, s54, v[4:5]
	v_cndmask_b32_e32 v3, v180, v176, vcc
	v_cndmask_b32_e32 v4, v182, v178, vcc
	v_cndmask_b32_e32 v173, v183, v180, vcc
	v_cndmask_b32_e64 v171, v4, v3, s[0:1]
	v_cndmask_b32_e64 v4, v173, v4, s[0:1]
	v_cndmask_b32_e32 v173, v178, v174, vcc
	v_cndmask_b32_e64 v3, v3, v173, s[0:1]
	v_sub_u32_e32 v175, 32, v147
	v_cmp_eq_u32_e64 s[14:15], 0, v147
	v_cndmask_b32_e32 v147, v176, v170, vcc
	v_cndmask_b32_e64 v4, v4, v171, s[12:13]
	v_cndmask_b32_e64 v171, v171, v3, s[12:13]
	v_cndmask_b32_e64 v170, v173, v147, s[0:1]
	v_alignbit_b32 v177, v4, v171, v175
	v_cndmask_b32_e64 v3, v3, v170, s[12:13]
	v_cndmask_b32_e64 v4, v177, v4, s[14:15]
	v_alignbit_b32 v173, v171, v3, v175
	v_cndmask_b32_e32 v2, v174, v2, vcc
	v_cndmask_b32_e64 v171, v173, v171, s[14:15]
	v_bfe_u32 v177, v4, 29, 1
	v_cndmask_b32_e64 v2, v147, v2, s[0:1]
	v_alignbit_b32 v173, v4, v171, 30
	v_sub_u32_e32 v178, 0, v177
	v_cndmask_b32_e64 v2, v170, v2, s[12:13]
	v_xor_b32_e32 v173, v173, v178
	v_alignbit_b32 v147, v3, v2, v175
	v_cndmask_b32_e64 v3, v147, v3, s[14:15]
	v_ffbh_u32_e32 v170, v173
	v_alignbit_b32 v147, v171, v3, 30
	v_min_u32_e32 v170, 32, v170
	v_alignbit_b32 v2, v3, v2, 30
	v_xor_b32_e32 v147, v147, v178
	v_sub_u32_e32 v171, 31, v170
	v_xor_b32_e32 v2, v2, v178
	v_alignbit_b32 v173, v173, v147, v171
	v_alignbit_b32 v2, v147, v2, v171
	v_alignbit_b32 v3, v173, v2, 9
	v_ffbh_u32_e32 v147, v3
	v_min_u32_e32 v147, 32, v147
	v_lshrrev_b32_e32 v176, 29, v4
	v_not_b32_e32 v171, v147
	v_alignbit_b32 v2, v3, v2, v171
	v_lshlrev_b32_e32 v3, 31, v176
	v_or_b32_e32 v171, 0x33000000, v3
	v_add_lshl_u32 v147, v147, v170, 23
	v_lshrrev_b32_e32 v2, 9, v2
	v_sub_u32_e32 v147, v171, v147
	v_or_b32_e32 v3, 0.5, v3
	v_lshlrev_b32_e32 v170, 23, v170
	v_or_b32_e32 v2, v147, v2
	v_lshrrev_b32_e32 v147, 9, v173
	v_sub_u32_e32 v3, v3, v170
	v_or_b32_e32 v3, v147, v3
	v_mul_f32_e32 v147, 0x3fc90fda, v3
	v_fma_f32 v170, v3, s55, -v147
	v_fmac_f32_e32 v170, 0x33a22168, v3
	v_fmac_f32_e32 v170, 0x3fc90fda, v2
	v_lshrrev_b32_e32 v2, 30, v4
	v_add_f32_e32 v3, v147, v170
	v_add_u32_e32 v2, v177, v2
; __device__ __forceinline__ void p0_job(const Params& p, char* smem, int job) {
;     ...
;       h1s[tg * 64 + j] = sinf(fr * a);
;       __syncthreads();
;       float a2 = b2;
;       for (int i = 0; i < 64; ++i) a2 += h1s[tg * 64 + i] * w2[i * 64 + j];
;       ((float*)(ws + OFF_HYH))[((size_t)l * 8448 + (Lsel ? 8192 : 0) + t) * 64 + j] = sinf(fr * a2);
.LBB0_56:
	s_andn2_saveexec_b64 s[0:1], s[26:27]
	v_mul_f32_e64 v2, |v0|, s56
	v_rndne_f32_e32 v4, v2
	v_cvt_i32_f32_e32 v2, v4
	v_fma_f32 v3, v4, s57, |v0|
	v_fmac_f32_e32 v3, 0xb3a22168, v4
	v_fmac_f32_e32 v3, 0xa7c234c4, v4
	s_or_b64 exec, exec, s[0:1]
	v_mul_f32_e32 v4, v3, v3
	v_fmamk_f32 v147, v4, 0xb94c1982, v150
	v_fmaak_f32 v147, v4, v147, 0xbe2aaa9d
	v_mul_f32_e32 v147, v4, v147
	v_fmac_f32_e32 v3, v3, v147
	v_fmamk_f32 v147, v4, 0x37d75334, v151
	v_fmaak_f32 v147, v4, v147, 0x3d2aabf7
	v_fmaak_f32 v147, v4, v147, 0xbf000004
	v_fma_f32 v4, v4, v147, 1.0
	v_and_b32_e32 v147, 1, v2
	v_lshlrev_b32_e32 v2, 30, v2
	v_cmp_eq_u32_e32 vcc, 0, v147
	v_and_b32_e32 v2, 0x80000000, v2
	v_xor_b32_e32 v1, v1, v0
	v_cndmask_b32_e32 v3, v4, v3, vcc
	v_xor_b32_e32 v1, v1, v2
	v_xor_b32_e32 v1, v1, v3
	v_cmp_class_f32_e64 vcc, v0, s59
	s_nop 1
	v_cndmask_b32_e32 v0, v158, v1, vcc
	ds_write_b32 v167, v0 offset:576
	s_waitcnt lgkmcnt(0)
	s_barrier
	ds_read_b128 v[0:3], v168 offset:576
	ds_read_b128 v[174:177], v168 offset:592
	ds_read_b128 v[178:181], v168 offset:608
	ds_read_b128 v[182:185], v168 offset:624
	global_load_dword v240, v[46:47], off
	global_load_dword v241, v[48:49], off
	global_load_dword v242, v[46:47], off offset:256
	global_load_dword v243, v[46:47], off offset:512
	global_load_dword v244, v[46:47], off offset:768
	global_load_dword v245, v[46:47], off offset:1024
	global_load_dword v246, v[46:47], off offset:1280
	global_load_dword v247, v[46:47], off offset:1536
	global_load_dword v248, v[46:47], off offset:1792
	global_load_dword v249, v[46:47], off offset:2048
	global_load_dword v250, v[46:47], off offset:2304
	global_load_dword v251, v[46:47], off offset:2560
	global_load_dword v252, v[46:47], off offset:2816
	global_load_dword v253, v[46:47], off offset:3072
	global_load_dword v254, v[46:47], off offset:3328
	global_load_dword v255, v[46:47], off offset:3584
	s_waitcnt vmcnt(0)
	s_waitcnt lgkmcnt(3)
	v_fma_f32 v4, v0, v240, v163
	v_fmac_f32_e32 v4, v1, v242
	v_fmac_f32_e32 v4, v2, v243
	v_fmac_f32_e32 v4, v3, v244
	s_waitcnt lgkmcnt(2)
	v_fmac_f32_e32 v4, v174, v245
	v_fmac_f32_e32 v4, v175, v246
	v_fmac_f32_e32 v4, v176, v247
	v_fmac_f32_e32 v4, v177, v248
	s_waitcnt lgkmcnt(1)
	v_fmac_f32_e32 v4, v178, v249
	v_fmac_f32_e32 v4, v179, v250
	v_fmac_f32_e32 v4, v180, v251
	v_fmac_f32_e32 v4, v181, v252
	s_waitcnt lgkmcnt(0)
	v_fmac_f32_e32 v4, v182, v253
	v_fmac_f32_e32 v4, v183, v254
	v_fmac_f32_e32 v4, v184, v255
	global_load_dword v240, v[46:47], off offset:3840
	global_load_dword v242, v[50:51], off
	global_load_dword v243, v[56:57], off
	global_load_dword v244, v[52:53], off
	global_load_dword v245, v[54:55], off
	global_load_dword v246, v[58:59], off
	global_load_dword v247, v[64:65], off
	global_load_dword v248, v[60:61], off
	global_load_dword v249, v[62:63], off
	global_load_dword v250, v[66:67], off
	global_load_dword v251, v[72:73], off
	global_load_dword v252, v[68:69], off
	global_load_dword v253, v[70:71], off
	global_load_dword v254, v[74:75], off
	s_waitcnt vmcnt(0)
	v_fmac_f32_e32 v4, v185, v240
	ds_read_b128 v[0:3], v168 offset:640
	s_waitcnt lgkmcnt(0)
	v_fmac_f32_e32 v4, v0, v241
	v_fmac_f32_e32 v4, v1, v242
	v_fmac_f32_e32 v4, v2, v244
	v_fmac_f32_e32 v4, v3, v245
	ds_read_b128 v[0:3], v168 offset:656
	s_waitcnt lgkmcnt(0)
	v_fmac_f32_e32 v4, v0, v243
	v_fmac_f32_e32 v4, v1, v246
	v_fmac_f32_e32 v4, v2, v248
	v_fmac_f32_e32 v4, v3, v249
	ds_read_b128 v[0:3], v168 offset:672
	s_waitcnt lgkmcnt(0)
	v_fmac_f32_e32 v4, v0, v247
	v_fmac_f32_e32 v4, v1, v250
	v_fmac_f32_e32 v4, v2, v252
	v_fmac_f32_e32 v4, v3, v253
	ds_read_b128 v[0:3], v168 offset:688
	s_waitcnt lgkmcnt(0)
	v_fmac_f32_e32 v4, v0, v251
	global_load_dword v255, v[80:81], off
	global_load_dword v240, v[76:77], off
	global_load_dword v241, v[78:79], off
	global_load_dword v242, v[84:85], off
	global_load_dword v243, v[90:91], off
	global_load_dword v244, v[86:87], off
	global_load_dword v245, v[88:89], off
	global_load_dword v246, v[92:93], off
	global_load_dword v247, v[98:99], off
	global_load_dword v248, v[94:95], off
	global_load_dword v249, v[96:97], off
	global_load_dword v250, v[100:101], off
	global_load_dword v252, v[106:107], off
	global_load_dword v253, v[102:103], off
	s_waitcnt vmcnt(0)
	v_fmac_f32_e32 v4, v1, v254
	v_fmac_f32_e32 v4, v2, v240
	v_fmac_f32_e32 v4, v3, v241
	ds_read_b128 v[0:3], v168 offset:704
	s_waitcnt lgkmcnt(0)
	v_fmac_f32_e32 v4, v0, v255
	v_fmac_f32_e32 v4, v1, v242
	v_fmac_f32_e32 v4, v2, v244
	v_fmac_f32_e32 v4, v3, v245
	ds_read_b128 v[0:3], v168 offset:720
	s_waitcnt lgkmcnt(0)
	v_fmac_f32_e32 v4, v0, v243
	v_fmac_f32_e32 v4, v1, v246
	v_fmac_f32_e32 v4, v2, v248
	v_fmac_f32_e32 v4, v3, v249
	ds_read_b128 v[0:3], v168 offset:736
	s_waitcnt lgkmcnt(0)
	v_fmac_f32_e32 v4, v0, v247
	v_fmac_f32_e32 v4, v1, v250
	v_fmac_f32_e32 v4, v2, v253
	global_load_dword v240, v[104:105], off
	global_load_dword v241, v[108:109], off
	global_load_dword v242, v[114:115], off
	global_load_dword v243, v[110:111], off
	global_load_dword v244, v[112:113], off
	global_load_dword v245, v[116:117], off
	global_load_dword v246, v[122:123], off
	global_load_dword v247, v[118:119], off
	global_load_dword v248, v[120:121], off
	global_load_dword v249, v[124:125], off
	global_load_dword v250, v[126:127], off
	global_load_dword v251, v[128:129], off
	global_load_dword v254, v[130:131], off
	global_load_dword v255, v[132:133], off
	s_waitcnt vmcnt(0)
	v_fmac_f32_e32 v4, v3, v240
	ds_read_b128 v[0:3], v168 offset:752
	s_waitcnt lgkmcnt(0)
	v_fmac_f32_e32 v4, v0, v252
	v_fmac_f32_e32 v4, v1, v241
	v_fmac_f32_e32 v4, v2, v243
	v_fmac_f32_e32 v4, v3, v244
	ds_read_b128 v[0:3], v168 offset:768
	s_waitcnt lgkmcnt(0)
	v_fmac_f32_e32 v4, v0, v242
	v_fmac_f32_e32 v4, v1, v245
	v_fmac_f32_e32 v4, v2, v247
	v_fmac_f32_e32 v4, v3, v248
	ds_read_b128 v[0:3], v168 offset:784
	s_waitcnt lgkmcnt(0)
	v_fmac_f32_e32 v4, v0, v246
	v_fmac_f32_e32 v4, v1, v249
	v_pk_mul_f32 v[0:1], v[2:3], v[250:251]
	s_nop 0
	v_add_f32_e32 v0, v4, v0
	v_add_f32_e32 v4, v0, v1
	ds_read_b128 v[0:3], v168 offset:800
	s_waitcnt lgkmcnt(0)
	v_pk_mul_f32 v[0:1], v[0:1], v[254:255]
	s_nop 0
	v_add_f32_e32 v0, v4, v0
	v_add_f32_e32 v4, v0, v1
	global_load_dword v240, v[134:135], off
	global_load_dword v241, v[136:137], off
	global_load_dword v242, v[138:139], off
	global_load_dword v243, v[140:141], off
	global_load_dword v244, v[142:143], off
	global_load_dword v245, v[144:145], off
	s_waitcnt vmcnt(0)
	v_pk_mul_f32 v[0:1], v[2:3], v[240:241]
	s_nop 0
	v_add_f32_e32 v0, v4, v0
	v_add_f32_e32 v4, v0, v1
	ds_read_b128 v[0:3], v168 offset:816
	s_waitcnt lgkmcnt(0)
	v_pk_mul_f32 v[0:1], v[0:1], v[242:243]
	s_nop 0
	v_add_f32_e32 v0, v4, v0
	v_add_f32_e32 v4, v0, v1
	v_pk_mul_f32 v[0:1], v[2:3], v[244:245]
	s_nop 0
	v_add_f32_e32 v0, v4, v0
	v_add_f32_e32 v0, v0, v1
	v_mul_f32_e32 v0, v164, v0
	v_and_b32_e32 v1, 0x7fffffff, v0
	v_cmp_nlt_f32_e64 s[0:1], |v0|, s47
	s_and_saveexec_b64 s[10:11], s[0:1]
	s_xor_b64 s[26:27], exec, s[10:11]
	s_cbranch_execz .LBB0_60
; __device__ __forceinline__ void p0_job(const Params& p, char* smem, int job) {
;     ...
;       ((float*)(ws + OFF_HYH))[((size_t)l * 8448 + (Lsel ? 8192 : 0) + t) * 64 + j] = sinf(fr * a2);
	v_lshrrev_b32_e32 v2, 23, v1
	v_add_u32_e32 v2, 0xffffff88, v2
	v_cmp_lt_u32_e32 vcc, 63, v2
	s_nop 1
	v_cndmask_b32_e32 v3, 0, v156, vcc
	v_add_u32_e32 v2, v3, v2
	v_cmp_lt_u32_e64 s[0:1], 31, v2
	s_nop 1
	v_cndmask_b32_e64 v3, 0, v157, s[0:1]
	v_add_u32_e32 v2, v3, v2
	v_cmp_lt_u32_e64 s[12:13], 31, v2
	s_nop 1
	v_cndmask_b32_e64 v3, 0, v157, s[12:13]
	v_add_u32_e32 v147, v3, v2
	v_and_b32_e32 v2, 0x7fffff, v1
	v_or_b32_e32 v173, 0x800000, v2
	v_mad_u64_u32 v[2:3], s[10:11], v173, s48, 0
	v_mov_b32_e32 v4, v3
	v_mad_u64_u32 v[170:171], s[10:11], v173, s49, v[4:5]
	v_mov_b32_e32 v4, v171
	v_mad_u64_u32 v[174:175], s[10:11], v173, s50, v[4:5]
	v_mov_b32_e32 v4, v175
	v_mad_u64_u32 v[176:177], s[10:11], v173, s51, v[4:5]
	v_mov_b32_e32 v4, v177
	v_mad_u64_u32 v[178:179], s[10:11], v173, s52, v[4:5]
	v_mov_b32_e32 v4, v179
	v_mad_u64_u32 v[180:181], s[10:11], v173, s53, v[4:5]
	v_mov_b32_e32 v4, v181
	v_mad_u64_u32 v[182:183], s[10:11], v173, s54, v[4:5]
	v_cndmask_b32_e32 v3, v180, v176, vcc
	v_cndmask_b32_e32 v4, v182, v178, vcc
	v_cndmask_b32_e32 v173, v183, v180, vcc
	v_cndmask_b32_e64 v171, v4, v3, s[0:1]
	v_cndmask_b32_e64 v4, v173, v4, s[0:1]
	v_cndmask_b32_e32 v173, v178, v174, vcc
	v_cndmask_b32_e64 v3, v3, v173, s[0:1]
	v_sub_u32_e32 v175, 32, v147
	v_cmp_eq_u32_e64 s[14:15], 0, v147
	v_cndmask_b32_e32 v147, v176, v170, vcc
	v_cndmask_b32_e64 v4, v4, v171, s[12:13]
	v_cndmask_b32_e64 v171, v171, v3, s[12:13]
	v_cndmask_b32_e64 v170, v173, v147, s[0:1]
	v_alignbit_b32 v177, v4, v171, v175
	v_cndmask_b32_e64 v3, v3, v170, s[12:13]
	v_cndmask_b32_e64 v4, v177, v4, s[14:15]
	v_alignbit_b32 v173, v171, v3, v175
	v_cndmask_b32_e32 v2, v174, v2, vcc
	v_cndmask_b32_e64 v171, v173, v171, s[14:15]
	v_bfe_u32 v177, v4, 29, 1
	v_cndmask_b32_e64 v2, v147, v2, s[0:1]
	v_alignbit_b32 v173, v4, v171, 30
	v_sub_u32_e32 v178, 0, v177
	v_cndmask_b32_e64 v2, v170, v2, s[12:13]
	v_xor_b32_e32 v173, v173, v178
	v_alignbit_b32 v147, v3, v2, v175
	v_cndmask_b32_e64 v3, v147, v3, s[14:15]
	v_ffbh_u32_e32 v170, v173
	v_alignbit_b32 v147, v171, v3, 30
	v_min_u32_e32 v170, 32, v170
	v_alignbit_b32 v2, v3, v2, 30
	v_xor_b32_e32 v147, v147, v178
	v_sub_u32_e32 v171, 31, v170
	v_xor_b32_e32 v2, v2, v178
	v_alignbit_b32 v173, v173, v147, v171
	v_alignbit_b32 v2, v147, v2, v171
	v_alignbit_b32 v3, v173, v2, 9
	v_ffbh_u32_e32 v147, v3
	v_min_u32_e32 v147, 32, v147
	v_lshrrev_b32_e32 v176, 29, v4
	v_not_b32_e32 v171, v147
	v_alignbit_b32 v2, v3, v2, v171
	v_lshlrev_b32_e32 v3, 31, v176
	v_or_b32_e32 v171, 0x33000000, v3
	v_add_lshl_u32 v147, v147, v170, 23
	v_lshrrev_b32_e32 v2, 9, v2
	v_sub_u32_e32 v147, v171, v147
	v_or_b32_e32 v3, 0.5, v3
	v_lshlrev_b32_e32 v170, 23, v170
	v_or_b32_e32 v2, v147, v2
	v_lshrrev_b32_e32 v147, 9, v173
	v_sub_u32_e32 v3, v3, v170
	v_or_b32_e32 v3, v147, v3
	v_mul_f32_e32 v147, 0x3fc90fda, v3
	v_fma_f32 v170, v3, s55, -v147
	v_fmac_f32_e32 v170, 0x33a22168, v3
	v_fmac_f32_e32 v170, 0x3fc90fda, v2
	v_lshrrev_b32_e32 v2, 30, v4
	v_add_f32_e32 v3, v147, v170
	v_add_u32_e32 v2, v177, v2

; __device__ __forceinline__ void p0_job(const Params& p, char* smem, int job) {
;     ...
;     int cj = tid & 63, ks = tid >> 6, col = cch * 64 + cj;
;     const float* W = p.w_mod + (size_t)l * 1024 * 6144;
;     float a0 = 0.f, a1 = 0.f, a2 = 0.f;
;     for (int k = ks * 256; k < ks * 256 + 256; ++k) {
;       float w = W[(size_t)k * 6144 + col];
;       a0 += sv[k] * w; a1 += sv[1024 + k] * w; a2 += sv[2048 + k] * w;
;     }
;     __syncthreads();
;     sv[(ks * 3 + 0) * 64 + cj] = a0; sv[(ks * 3 + 1) * 64 + cj] = a1; sv[(ks * 3 + 2) * 64 + cj] = a2;
;     __syncthreads();
;     if (ks < 3) {
;       int v = ks;
;       float s = sv[(0 * 3 + v) * 64 + cj] + sv[(1 * 3 + v) * 64 + cj] + sv[(2 * 3 + v) * 64 + cj] + sv[(3 * 3 + v) * 64 + cj];
;       ((float*)(ws + OFF_MODS))[(l * 3 + v) * 6144 + col] = s + p.b_mod[l * 6144 + col];
.LBB0_89:
	v_lshl_add_u64 v[24:25], v[8:9], 0, s[0:1]
	global_load_dword v240, v[24:25], off
	v_add_co_u32_e32 v26, vcc, 0x6000, v24
	s_nop 1
	v_addc_co_u32_e32 v27, vcc, 0, v25, vcc
	global_load_dword v241, v[26:27], off
	v_add_co_u32_e32 v26, vcc, 0xc000, v24
	s_nop 1
	v_addc_co_u32_e32 v27, vcc, 0, v25, vcc
	global_load_dword v242, v[26:27], off
	v_add_co_u32_e32 v26, vcc, 0x12000, v24
	s_nop 1
	v_addc_co_u32_e32 v27, vcc, 0, v25, vcc
	global_load_dword v243, v[26:27], off
	v_add_co_u32_e32 v26, vcc, 0x18000, v24
	s_nop 1
	v_addc_co_u32_e32 v27, vcc, 0, v25, vcc
	global_load_dword v244, v[26:27], off
	v_add_co_u32_e32 v26, vcc, 0x1e000, v24
	s_nop 1
	v_addc_co_u32_e32 v27, vcc, 0, v25, vcc
	global_load_dword v245, v[26:27], off
	v_add_co_u32_e32 v26, vcc, 0x24000, v24
	s_nop 1
	v_addc_co_u32_e32 v27, vcc, 0, v25, vcc
	global_load_dword v246, v[26:27], off
	v_add_co_u32_e32 v26, vcc, 0x2a000, v24
	s_nop 1
	v_addc_co_u32_e32 v27, vcc, 0, v25, vcc
	global_load_dword v247, v[26:27], off
	v_add_co_u32_e32 v26, vcc, 0x30000, v24
	s_nop 1
	v_addc_co_u32_e32 v27, vcc, 0, v25, vcc
	global_load_dword v248, v[26:27], off
	v_add_co_u32_e32 v26, vcc, 0x36000, v24
	s_nop 1
	v_addc_co_u32_e32 v27, vcc, 0, v25, vcc
	global_load_dword v249, v[26:27], off
	v_add_co_u32_e32 v26, vcc, 0x3c000, v24
	s_nop 1
	v_addc_co_u32_e32 v27, vcc, 0, v25, vcc
	global_load_dword v250, v[26:27], off
	v_add_co_u32_e32 v26, vcc, 0x42000, v24
	s_nop 1
	v_addc_co_u32_e32 v27, vcc, 0, v25, vcc
	global_load_dword v251, v[26:27], off
	v_add_co_u32_e32 v26, vcc, 0x48000, v24
	s_nop 1
	v_addc_co_u32_e32 v27, vcc, 0, v25, vcc
	global_load_dword v252, v[26:27], off
	v_add_co_u32_e32 v26, vcc, 0x4e000, v24
	s_nop 1
	v_addc_co_u32_e32 v27, vcc, 0, v25, vcc
	global_load_dword v253, v[26:27], off
	v_add_co_u32_e32 v26, vcc, 0x54000, v24
	s_nop 1
	v_addc_co_u32_e32 v27, vcc, 0, v25, vcc
	global_load_dword v254, v[26:27], off
	v_add_co_u32_e32 v26, vcc, 0x5a000, v24
	s_nop 1
	v_addc_co_u32_e32 v27, vcc, 0, v25, vcc
	global_load_dword v255, v[26:27], off
	s_add_u32 s0, s0, 0x60000
	s_addc_u32 s1, s1, 0
	s_waitcnt vmcnt(0)
	ds_read_b128 v[12:15], v7
	ds_read_b128 v[16:19], v7 offset:4096
	ds_read_b128 v[20:23], v7 offset:8192
	v_add_u32_e32 v7, 16, v7
	s_waitcnt lgkmcnt(0)
	v_fmac_f32_e32 v10, v240, v12
	v_fmac_f32_e32 v11, v240, v16
	v_fmac_f32_e32 v1, v240, v20
	v_fmac_f32_e32 v10, v241, v13
	v_fmac_f32_e32 v11, v241, v17
	v_fmac_f32_e32 v1, v241, v21
	v_fmac_f32_e32 v10, v242, v14
	v_fmac_f32_e32 v11, v242, v18
	v_fmac_f32_e32 v1, v242, v22
	v_fmac_f32_e32 v10, v243, v15
	v_fmac_f32_e32 v11, v243, v19
	v_fmac_f32_e32 v1, v243, v23
	ds_read_b128 v[12:15], v7
	ds_read_b128 v[16:19], v7 offset:4096
	ds_read_b128 v[20:23], v7 offset:8192
	v_add_u32_e32 v7, 16, v7
	s_waitcnt lgkmcnt(0)
	v_fmac_f32_e32 v10, v244, v12
	v_fmac_f32_e32 v11, v244, v16
	v_fmac_f32_e32 v1, v244, v20
	v_fmac_f32_e32 v10, v245, v13
	v_fmac_f32_e32 v11, v245, v17
	v_fmac_f32_e32 v1, v245, v21
	v_fmac_f32_e32 v10, v246, v14
	v_fmac_f32_e32 v11, v246, v18
	v_fmac_f32_e32 v1, v246, v22
	v_fmac_f32_e32 v10, v247, v15
	v_fmac_f32_e32 v11, v247, v19
	v_fmac_f32_e32 v1, v247, v23
	ds_read_b128 v[12:15], v7
	ds_read_b128 v[16:19], v7 offset:4096
	ds_read_b128 v[20:23], v7 offset:8192
	v_add_u32_e32 v7, 16, v7
	s_waitcnt lgkmcnt(0)
	v_fmac_f32_e32 v10, v248, v12
	v_fmac_f32_e32 v11, v248, v16
	v_fmac_f32_e32 v1, v248, v20
	v_fmac_f32_e32 v10, v249, v13
	v_fmac_f32_e32 v11, v249, v17
	v_fmac_f32_e32 v1, v249, v21
	v_fmac_f32_e32 v10, v250, v14
	v_fmac_f32_e32 v11, v250, v18
	v_fmac_f32_e32 v1, v250, v22
	v_fmac_f32_e32 v10, v251, v15
	v_fmac_f32_e32 v11, v251, v19
	v_fmac_f32_e32 v1, v251, v23
	ds_read_b128 v[12:15], v7
	ds_read_b128 v[16:19], v7 offset:4096
	ds_read_b128 v[20:23], v7 offset:8192
	v_add_u32_e32 v7, 16, v7
	s_waitcnt lgkmcnt(0)
	v_fmac_f32_e32 v10, v252, v12
	v_fmac_f32_e32 v11, v252, v16
	v_fmac_f32_e32 v1, v252, v20
	v_fmac_f32_e32 v10, v253, v13
	v_fmac_f32_e32 v11, v253, v17
	v_fmac_f32_e32 v1, v253, v21
	v_fmac_f32_e32 v10, v254, v14
	v_fmac_f32_e32 v11, v254, v18
	v_fmac_f32_e32 v1, v254, v22
	v_fmac_f32_e32 v10, v255, v15
	v_fmac_f32_e32 v11, v255, v19
	v_fmac_f32_e32 v1, v255, v23
	s_cmp_eq_u32 s0, 0x600000
	s_cbranch_scc0 .LBB0_89
	s_movk_i32 s0, 0x300
	v_mul_lo_u32 v7, v2, s0
	v_lshl_or_b32 v7, v4, 2, v7
	v_cmp_gt_i32_e32 vcc, 3, v2
	s_barrier
	ds_write2st64_b32 v7, v10, v11 offset1:1
	ds_write_b32 v7, v1 offset:512
	s_waitcnt lgkmcnt(0)
	s_barrier
	s_and_saveexec_b64 s[0:1], vcc
	s_cbranch_execz .LBB0_92
	s_mov_b32 s4, 0x3fffffc0
	ds_read_b32 v1, v3
	v_and_or_b32 v3, v6, s4, v4
	v_lshlrev_b32_e32 v3, 2, v3
	ds_read2st64_b32 v[6:7], v3 offset0:3 offset1:6
	ds_read_b32 v3, v3 offset:2304
	s_mul_i32 s4, s2, 0x1800
	v_readlane_b32 s68, v239, 7
	v_readlane_b32 s78, v239, 17
	s_waitcnt lgkmcnt(1)
	v_add_f32_e32 v1, v1, v6
	v_add_u32_e32 v6, s4, v0
	v_add_f32_e32 v1, v1, v7
	v_ashrrev_i32_e32 v7, 31, v6
	v_readlane_b32 s79, v239, 18
	s_waitcnt lgkmcnt(0)
	v_add_f32_e32 v1, v1, v3
	v_readlane_b32 s69, v239, 8
	v_lshl_add_u64 v[6:7], v[6:7], 2, s[78:79]
	global_load_dword v3, v[6:7], off
	v_readlane_b32 s70, v239, 9
	v_readlane_b32 s71, v239, 10
	v_readlane_b32 s72, v239, 11
	v_readlane_b32 s73, v239, 12
	v_readlane_b32 s74, v239, 13
	v_readlane_b32 s75, v239, 14
	v_readlane_b32 s76, v239, 15
	v_readlane_b32 s77, v239, 16
	v_readlane_b32 s80, v239, 19
	v_readlane_b32 s81, v239, 20
	v_readlane_b32 s82, v239, 21
	v_readlane_b32 s83, v239, 22
	s_waitcnt vmcnt(0)
	v_add_f32_e32 v4, v1, v3
	v_mad_u64_u32 v[2:3], s[4:5], s2, 3, v[2:3]
	s_movk_i32 s2, 0x1800
	v_mad_u64_u32 v[0:1], s[4:5], v2, s2, v[0:1]
	v_ashrrev_i32_e32 v1, 31, v0
	v_lshl_add_u64 v[0:1], v[0:1], 2, s[20:21]
	v_add_co_u32_e32 v0, vcc, 0x18e00000, v0
	s_nop 1
	v_addc_co_u32_e32 v1, vcc, 0, v1, vcc
	global_store_dword v[0:1], v4, off

; __device__ __forceinline__ float bf2f(u16 h) { return __uint_as_float(((unsigned)h) << 16); }
; __device__ __forceinline__ unsigned pack2(float a, float b) { return (unsigned)f2bf(a) | ((unsigned)f2bf(b) << 16); }
; __device__ __forceinline__ void hyena_lat_job(const Params& p, char* smem, int l, int c) {
;     ...
;     for (int i4 = tid; i4 < 4096; i4 += 256) {
;       int i = i4 * 4;
;       int b = i >> 13, t = i & 8191;
;       uint2 mid = *(const uint2*)&u[i];
;       float um = t > 0 ? bf2f(u[i - 1]) : 0.f, up = t + 4 < 8192 ? bf2f(u[i + 4]) : 0.f;
;       float e0 = __uint_as_float(mid.x << 16), e1 = __uint_as_float(mid.x & 0xffff0000u);
;       float e2 = __uint_as_float(mid.y << 16), e3 = __uint_as_float(mid.y & 0xffff0000u);
;       float z0 = bb + w0 * um + w1 * e0 + w2 * e1;
;       float z1 = bb + w0 * e0 + w1 * e1 + w2 * e2;
;       float z2 = bb + w0 * e1 + w1 * e2 + w2 * e3;
;       float z3 = bb + w0 * e2 + w1 * e3 + w2 * up;
;       uint2 o; o.x = pack2(z0, z1); o.y = pack2(z2, z3);
;       *(uint2*)&zs[b * 10240 + (t >> 5) * 40 + (t & 31)] = o;
;     }
.LBB0_976:
	s_or_b64 exec, exec, s[18:19]
	v_ashrrev_i32_e32 v19, 11, v18
	v_lshrrev_b32_e32 v13, 5, v13
	v_and_b32_e32 v20, 28, v10
	s_waitcnt vmcnt(0) lgkmcnt(0)
	v_lshlrev_b32_e32 v12, 16, v12
	v_lshlrev_b32_e32 v11, 16, v11
	v_lshlrev_b32_e32 v16, 16, v14
	v_and_b32_e32 v17, 0xffff0000, v15
	v_and_b32_e32 v14, 0xffff0000, v14
	v_lshlrev_b32_e32 v15, 16, v15
	v_mul_i32_i24_e32 v19, 0x5000, v19
	v_mul_u32_u24_e32 v13, 0x50, v13
	v_lshlrev_b32_e32 v20, 1, v20
	v_add3_u32 v19, v19, v13, v20
	v_mov_b32_e32 v20, v16
	v_mov_b32_e32 v21, v14
	v_mov_b32_e32 v13, v15
	v_pk_fma_f32 v[20:21], v[2:3], v[20:21], v[8:9]
	v_pk_fma_f32 v[12:13], v[2:3], v[12:13], v[8:9]
	v_mov_b32_e32 v22, v15
	v_pk_fma_f32 v[20:21], v[4:5], v[14:15], v[20:21]
	v_pk_fma_f32 v[12:13], v[4:5], v[16:17], v[12:13]
	v_mov_b32_e32 v15, v11
	v_mov_b32_e32 v23, v17
	v_pk_fma_f32 v[12:13], v[6:7], v[14:15], v[12:13]
	v_pk_fma_f32 v[20:21], v[6:7], v[22:23], v[20:21]
	v_and_b32_sdwa v15, v13, v198 dst_sel:DWORD dst_unused:UNUSED_PAD src0_sel:WORD_1 src1_sel:DWORD
	v_and_b32_sdwa v11, v21, v198 dst_sel:DWORD dst_unused:UNUSED_PAD src0_sel:WORD_1 src1_sel:DWORD
	v_and_b32_sdwa v14, v20, v198 dst_sel:DWORD dst_unused:UNUSED_PAD src0_sel:WORD_1 src1_sel:DWORD
	v_add3_u32 v13, v13, v15, s33
	v_add3_u32 v11, v21, v11, s33
	v_add3_u32 v14, v20, v14, s33
	v_and_b32_sdwa v16, v12, v198 dst_sel:DWORD dst_unused:UNUSED_PAD src0_sel:WORD_1 src1_sel:DWORD
	v_and_b32_e32 v13, 0xffff0000, v13
	s_movk_i32 s18, 0xeff
	v_and_b32_e32 v14, 0xffff0000, v14
	v_add3_u32 v12, v12, v16, s33
	v_or_b32_sdwa v13, v13, v11 dst_sel:DWORD dst_unused:UNUSED_PAD src0_sel:DWORD src1_sel:WORD_1
	v_add_u32_e32 v11, 0x100, v18
	v_cmp_lt_i32_e32 vcc, s18, v18
	v_or_b32_sdwa v12, v12, v14 dst_sel:DWORD dst_unused:UNUSED_PAD src0_sel:WORD_1 src1_sel:DWORD
	v_add_u32_e32 v10, 0x400, v10
	s_or_b64 s[16:17], vcc, s[16:17]
	v_mov_b32_e32 v18, v11
	ds_write_b64 v19, v[12:13]
	s_andn2_b64 exec, exec, s[16:17]
	s_cbranch_execz .LBB0_981
.LBB0_977:
	v_ashrrev_i32_e32 v11, 31, v10
	v_lshl_add_u64 v[16:17], v[10:11], 1, s[14:15]
	global_load_dwordx2 v[14:15], v[16:17], off
	v_and_b32_e32 v13, 0x1ffc, v10
	v_cmp_ne_u32_e32 vcc, 0, v13
	v_mov_b32_e32 v11, 0
	v_mov_b32_e32 v12, 0
	s_and_saveexec_b64 s[18:19], vcc
	global_load_ushort v12, v[16:17], off offset:-2
	s_or_b64 exec, exec, s[18:19]
	s_movk_i32 s18, 0x1ffc
	v_cmp_ne_u32_e32 vcc, s18, v13
	s_and_saveexec_b64 s[18:19], vcc
	global_load_ushort v11, v[16:17], off offset:8
	s_branch .LBB0_976

; __device__ __forceinline__ float bf2f(u16 h) { return __uint_as_float(((unsigned)h) << 16); }
; __device__ __forceinline__ unsigned pack2(float a, float b) { return (unsigned)f2bf(a) | ((unsigned)f2bf(b) << 16); }
; __device__ __forceinline__ void hyena_lat_job(const Params& p, char* smem, int l, int c) {
;     ...
;         int t0 = tb + 32 * mt + 8 * g;
;         float uu[6];
;         {
;           const uint2 mid = *(const uint2*)&u[t0];
;           uu[0] = t0 > 0 ? bf2f(u[t0 - 1]) : 0.f;
;           uu[1] = __uint_as_float(mid.x << 16); uu[2] = __uint_as_float(mid.x & 0xffff0000u);
;           uu[3] = __uint_as_float(mid.y << 16); uu[4] = __uint_as_float(mid.y & 0xffff0000u);
;           uu[5] = t0 + 4 < 8192 ? bf2f(u[t0 + 4]) : 0.f;
;         }
;         const int zi0 = b * 10240 + (t0 >> 5) * 40 + (t0 & 31);
;         const uint2 zo = *(const uint2*)&zs[zi0];
;         float zold4[4] = {__uint_as_float(zo.x << 16), __uint_as_float(zo.x & 0xffff0000u),
;                           __uint_as_float(zo.y << 16), __uint_as_float(zo.y & 0xffff0000u)};
;         float zn4[4];
; #pragma unroll
;         for (int q = 0; q < 4; ++q) {
;           float gate = bb + w0 * uu[q] + w1 * uu[q + 1] + w2 * uu[q + 2];
;           zn4[q] = gate * (scale * acc[mt][g * 4 + q] + zold4[q] * skip);
;         }
;         if (o == 0) {
;           uint2 zw; zw.x = pack2(zn4[0], zn4[1]); zw.y = pack2(zn4[2], zn4[3]);
;           *(uint2*)&zs[zi0] = zw;
;         } else {
; #pragma unroll
;           for (int q = 0; q < 4; ++q) MIX[(size_t)(b * 8192 + t0 + q) * 1024 + 512 + c] = f2bf(zn4[q]);
.LBB0_1025:
	global_load_dwordx2 v[52:53], v[76:77], off offset:16
	v_add_u32_e32 v0, 8, v78
	v_cmp_lt_i32_e32 vcc, -8, v78
	v_mov_b32_e32 v244, 0
	v_mov_b32_e32 v245, 0
	s_and_saveexec_b64 s[0:1], vcc
	v_lshl_add_u64 v[84:85], v[0:1], 1, v[80:81]
	v_add_co_u32_e32 v84, vcc, -2, v84
	s_nop 1
	v_addc_co_u32_e32 v85, vcc, -1, v85, vcc
	global_load_ushort v244, v[84:85], off
	s_or_b64 exec, exec, s[0:1]
	s_movk_i32 s0, 0x1ff4
	v_cmp_gt_i32_e32 vcc, s0, v78
	s_and_saveexec_b64 s[0:1], vcc
	global_load_ushort v245, v[76:77], off offset:24
	s_or_b64 exec, exec, s[0:1]
	s_waitcnt vmcnt(0) lgkmcnt(0)
	v_lshlrev_b32_e32 v84, 16, v244
	v_lshlrev_b32_e32 v51, 16, v245
	v_and_b32_e32 v50, 31, v0
	v_ashrrev_i32_e32 v85, 5, v0
	v_mul_lo_u32 v85, v85, s54
	v_lshlrev_b32_e32 v86, 1, v50
	v_add3_u32 v87, v130, v85, v86
	ds_read_b64 v[94:95], v87
	s_waitcnt vmcnt(0) lgkmcnt(0)
	v_and_b32_e32 v92, 0xffff0000, v52
	v_mov_b32_e32 v71, v70
	v_mov_b32_e32 v75, v74
	v_mov_b32_e32 v85, v92
	v_mov_b32_e32 v69, v68
	v_lshlrev_b32_e32 v90, 16, v52
	v_lshlrev_b32_e32 v91, 16, v53
	v_pk_fma_f32 v[84:85], v[70:71], v[84:85], v[74:75]
	v_mov_b32_e32 v67, v66
	v_and_b32_e32 v93, 0xffff0000, v53
	v_mov_b32_e32 v50, v91
	v_lshlrev_b32_e32 v53, 16, v95
	v_lshlrev_b32_e32 v52, 16, v94
	v_and_b32_e32 v95, 0xffff0000, v95
	v_and_b32_e32 v94, 0xffff0000, v94
	v_pk_fma_f32 v[84:85], v[68:69], v[90:91], v[84:85]
	v_pk_fma_f32 v[90:91], v[70:71], v[90:91], v[74:75]
	v_mov_b32_e32 v73, v72
	v_mov_b32_e32 v83, v82
	v_mov_b32_e32 v96, v54
	v_mov_b32_e32 v97, v56
	v_pk_mul_f32 v[52:53], v[66:67], v[52:53]
	v_pk_fma_f32 v[90:91], v[68:69], v[92:93], v[90:91]
	v_mov_b32_e32 v56, v55
	v_pk_mul_f32 v[54:55], v[66:67], v[94:95]
	v_pk_fma_f32 v[84:85], v[72:73], v[92:93], v[84:85]
	v_pk_fma_f32 v[52:53], v[96:97], v[82:83], v[52:53]
	v_pk_fma_f32 v[50:51], v[72:73], v[50:51], v[90:91]
	v_pk_fma_f32 v[54:55], v[56:57], v[82:83], v[54:55]
	v_pk_mul_f32 v[52:53], v[84:85], v[52:53]
	v_pk_mul_f32 v[50:51], v[50:51], v[54:55]
	s_and_b64 vcc, exec, s[50:51]
	s_mov_b64 s[0:1], -1
	s_cbranch_vccnz .LBB0_1031
	v_add_u32_e32 v54, v0, v128
	v_ashrrev_i32_e32 v55, 31, v54
	v_bfe_u32 v0, v52, 16, 1
	v_lshlrev_b64 v[54:55], 11, v[54:55]
	v_add3_u32 v0, v52, v0, s33
	v_lshl_add_u64 v[54:55], s[4:5], 0, v[54:55]
	global_store_short_d16_hi v[54:55], v0, off
	v_bfe_u32 v0, v50, 16, 1
	v_add3_u32 v0, v50, v0, s33
	global_store_short_d16_hi v[54:55], v0, off offset:2048
	v_bfe_u32 v0, v53, 16, 1
	v_add_co_u32_e32 v54, vcc, 0x1000, v54
	v_add3_u32 v0, v53, v0, s33
	s_nop 0
	v_addc_co_u32_e32 v55, vcc, 0, v55, vcc
	global_store_short_d16_hi v[54:55], v0, off
	v_bfe_u32 v0, v51, 16, 1
	v_add3_u32 v0, v51, v0, s33
	s_mov_b64 s[0:1], 0
	global_store_short_d16_hi v[54:55], v0, off offset:2048

; __device__ __forceinline__ float bf2f(u16 h) { return __uint_as_float(((unsigned)h) << 16); }
; __device__ __forceinline__ unsigned pack2(float a, float b) { return (unsigned)f2bf(a) | ((unsigned)f2bf(b) << 16); }
; __device__ __forceinline__ void hyena_lat_job(const Params& p, char* smem, int l, int c) {
;     ...
;         int t0 = tb + 32 * mt + 8 * g;
;         float uu[6];
;         {
;           const uint2 mid = *(const uint2*)&u[t0];
;           uu[0] = t0 > 0 ? bf2f(u[t0 - 1]) : 0.f;
;           uu[1] = __uint_as_float(mid.x << 16); uu[2] = __uint_as_float(mid.x & 0xffff0000u);
;           uu[3] = __uint_as_float(mid.y << 16); uu[4] = __uint_as_float(mid.y & 0xffff0000u);
;           uu[5] = t0 + 4 < 8192 ? bf2f(u[t0 + 4]) : 0.f;
;         }
;         const int zi0 = b * 10240 + (t0 >> 5) * 40 + (t0 & 31);
;         const uint2 zo = *(const uint2*)&zs[zi0];
;         float zold4[4] = {__uint_as_float(zo.x << 16), __uint_as_float(zo.x & 0xffff0000u),
;                           __uint_as_float(zo.y << 16), __uint_as_float(zo.y & 0xffff0000u)};
;         float zn4[4];
; #pragma unroll
;         for (int q = 0; q < 4; ++q) {
;           float gate = bb + w0 * uu[q] + w1 * uu[q + 1] + w2 * uu[q + 2];
;           zn4[q] = gate * (scale * acc[mt][g * 4 + q] + zold4[q] * skip);
;         }
;         if (o == 0) {
;           uint2 zw; zw.x = pack2(zn4[0], zn4[1]); zw.y = pack2(zn4[2], zn4[3]);
;           *(uint2*)&zs[zi0] = zw;
;         } else {
; #pragma unroll
;           for (int q = 0; q < 4; ++q) MIX[(size_t)(b * 8192 + t0 + q) * 1024 + 512 + c] = f2bf(zn4[q]);
.LBB0_1033:
	global_load_dwordx2 v[52:53], v[76:77], off offset:32
	v_add_u32_e32 v0, 16, v78
	v_cmp_lt_i32_e32 vcc, -16, v78
	v_mov_b32_e32 v244, 0
	v_mov_b32_e32 v245, 0
	s_and_saveexec_b64 s[0:1], vcc
	v_lshl_add_u64 v[54:55], v[0:1], 1, v[80:81]
	v_add_co_u32_e32 v54, vcc, -2, v54
	s_nop 1
	v_addc_co_u32_e32 v55, vcc, -1, v55, vcc
	global_load_ushort v244, v[54:55], off
	s_or_b64 exec, exec, s[0:1]
	s_movk_i32 s0, 0x1fec
	v_cmp_gt_i32_e32 vcc, s0, v78
	s_and_saveexec_b64 s[0:1], vcc
	global_load_ushort v245, v[76:77], off offset:40
	s_or_b64 exec, exec, s[0:1]
	s_waitcnt vmcnt(0) lgkmcnt(0)
	v_lshlrev_b32_e32 v54, 16, v244
	v_lshlrev_b32_e32 v51, 16, v245
	v_xor_b32_e32 v50, 16, v88
	v_ashrrev_i32_e32 v55, 5, v0
	v_mul_lo_u32 v55, v55, s54
	v_lshlrev_b32_e32 v56, 1, v50
	v_add3_u32 v57, v130, v55, v56
	ds_read_b64 v[90:91], v57
	s_waitcnt vmcnt(0) lgkmcnt(0)
	v_and_b32_e32 v88, 0xffff0000, v52
	v_mov_b32_e32 v55, v88
	v_lshlrev_b32_e32 v84, 16, v52
	v_lshlrev_b32_e32 v85, 16, v53
	v_pk_fma_f32 v[54:55], v[70:71], v[54:55], v[74:75]
	v_and_b32_e32 v89, 0xffff0000, v53
	v_mov_b32_e32 v50, v85
	v_lshlrev_b32_e32 v53, 16, v91
	v_lshlrev_b32_e32 v52, 16, v90
	v_and_b32_e32 v91, 0xffff0000, v91
	v_and_b32_e32 v90, 0xffff0000, v90
	v_pk_fma_f32 v[54:55], v[68:69], v[84:85], v[54:55]
	v_pk_fma_f32 v[84:85], v[70:71], v[84:85], v[74:75]
	v_mov_b32_e32 v92, v58
	v_mov_b32_e32 v93, v60
	v_pk_mul_f32 v[52:53], v[66:67], v[52:53]
	v_pk_fma_f32 v[84:85], v[68:69], v[88:89], v[84:85]
	v_mov_b32_e32 v60, v59
	v_pk_mul_f32 v[58:59], v[66:67], v[90:91]
	v_pk_fma_f32 v[54:55], v[72:73], v[88:89], v[54:55]
	v_pk_fma_f32 v[52:53], v[92:93], v[82:83], v[52:53]
	v_pk_fma_f32 v[50:51], v[72:73], v[50:51], v[84:85]
	v_pk_fma_f32 v[58:59], v[60:61], v[82:83], v[58:59]
	v_pk_mul_f32 v[52:53], v[54:55], v[52:53]
	v_pk_mul_f32 v[50:51], v[50:51], v[58:59]
	s_and_b64 vcc, exec, s[50:51]
	s_mov_b64 s[0:1], -1
	s_cbranch_vccnz .LBB0_1039
	v_add_u32_e32 v54, v0, v128
	v_ashrrev_i32_e32 v55, 31, v54
	v_bfe_u32 v0, v52, 16, 1
	v_lshlrev_b64 v[54:55], 11, v[54:55]
	v_add3_u32 v0, v52, v0, s33
	v_lshl_add_u64 v[54:55], s[4:5], 0, v[54:55]
	global_store_short_d16_hi v[54:55], v0, off
	v_bfe_u32 v0, v50, 16, 1
	v_add3_u32 v0, v50, v0, s33
	global_store_short_d16_hi v[54:55], v0, off offset:2048
	v_bfe_u32 v0, v53, 16, 1
	v_add_co_u32_e32 v54, vcc, 0x1000, v54
	v_add3_u32 v0, v53, v0, s33
	s_nop 0
	v_addc_co_u32_e32 v55, vcc, 0, v55, vcc
	global_store_short_d16_hi v[54:55], v0, off
	v_bfe_u32 v0, v51, 16, 1
	v_add3_u32 v0, v51, v0, s33
	s_mov_b64 s[0:1], 0
	global_store_short_d16_hi v[54:55], v0, off offset:2048

; __device__ __forceinline__ float bf2f(u16 h) { return __uint_as_float(((unsigned)h) << 16); }
; __device__ __forceinline__ unsigned pack2(float a, float b) { return (unsigned)f2bf(a) | ((unsigned)f2bf(b) << 16); }
; __device__ __forceinline__ void hyena_lat_job(const Params& p, char* smem, int l, int c) {
;     ...
;         int t0 = tb + 32 * mt + 8 * g;
;         float uu[6];
;         {
;           const uint2 mid = *(const uint2*)&u[t0];
;           uu[0] = t0 > 0 ? bf2f(u[t0 - 1]) : 0.f;
;           uu[1] = __uint_as_float(mid.x << 16); uu[2] = __uint_as_float(mid.x & 0xffff0000u);
;           uu[3] = __uint_as_float(mid.y << 16); uu[4] = __uint_as_float(mid.y & 0xffff0000u);
;           uu[5] = t0 + 4 < 8192 ? bf2f(u[t0 + 4]) : 0.f;
;         }
;         const int zi0 = b * 10240 + (t0 >> 5) * 40 + (t0 & 31);
;         const uint2 zo = *(const uint2*)&zs[zi0];
;         float zold4[4] = {__uint_as_float(zo.x << 16), __uint_as_float(zo.x & 0xffff0000u),
;                           __uint_as_float(zo.y << 16), __uint_as_float(zo.y & 0xffff0000u)};
;         float zn4[4];
; #pragma unroll
;         for (int q = 0; q < 4; ++q) {
;           float gate = bb + w0 * uu[q] + w1 * uu[q + 1] + w2 * uu[q + 2];
;           zn4[q] = gate * (scale * acc[mt][g * 4 + q] + zold4[q] * skip);
;         }
;         if (o == 0) {
;           uint2 zw; zw.x = pack2(zn4[0], zn4[1]); zw.y = pack2(zn4[2], zn4[3]);
;           *(uint2*)&zs[zi0] = zw;
;         } else {
; #pragma unroll
;           for (int q = 0; q < 4; ++q) MIX[(size_t)(b * 8192 + t0 + q) * 1024 + 512 + c] = f2bf(zn4[q]);
.LBB0_1041:
	global_load_dwordx2 v[52:53], v[76:77], off offset:48
	s_movk_i32 s0, 0xffe8
	v_add_u32_e32 v0, 24, v78
	v_cmp_lt_i32_e32 vcc, s0, v78
	v_mov_b32_e32 v244, 0
	v_mov_b32_e32 v245, 0
	s_and_saveexec_b64 s[0:1], vcc
	v_lshl_add_u64 v[54:55], v[0:1], 1, v[80:81]
	v_add_co_u32_e32 v54, vcc, -2, v54
	s_nop 1
	v_addc_co_u32_e32 v55, vcc, -1, v55, vcc
	global_load_ushort v244, v[54:55], off
	s_or_b64 exec, exec, s[0:1]
	s_movk_i32 s0, 0x1fe4
	v_cmp_gt_i32_e32 vcc, s0, v78
	s_and_saveexec_b64 s[0:1], vcc
	global_load_ushort v245, v[76:77], off offset:56
	s_or_b64 exec, exec, s[0:1]
	s_waitcnt vmcnt(0) lgkmcnt(0)
	v_lshlrev_b32_e32 v54, 16, v244
	v_lshlrev_b32_e32 v51, 16, v245
	v_and_b32_e32 v50, 31, v0
	v_ashrrev_i32_e32 v55, 5, v0
	v_mul_lo_u32 v55, v55, s54
	v_lshlrev_b32_e32 v57, 1, v50
	v_add3_u32 v58, v130, v55, v57
	ds_read_b64 v[88:89], v58
	s_waitcnt vmcnt(0) lgkmcnt(0)
	v_and_b32_e32 v84, 0xffff0000, v52
	v_mov_b32_e32 v55, v84
	v_lshlrev_b32_e32 v60, 16, v52
	v_lshlrev_b32_e32 v61, 16, v53
	v_pk_fma_f32 v[54:55], v[70:71], v[54:55], v[74:75]
	v_and_b32_e32 v85, 0xffff0000, v53
	v_mov_b32_e32 v50, v61
	v_pk_fma_f32 v[54:55], v[68:69], v[60:61], v[54:55]
	v_pk_fma_f32 v[60:61], v[70:71], v[60:61], v[74:75]
	v_lshlrev_b32_e32 v53, 16, v89
	v_lshlrev_b32_e32 v52, 16, v88
	v_and_b32_e32 v89, 0xffff0000, v89
	v_and_b32_e32 v88, 0xffff0000, v88
	v_pk_fma_f32 v[60:61], v[68:69], v[84:85], v[60:61]
	v_mov_b32_e32 v90, v62
	v_mov_b32_e32 v91, v64
	v_pk_mul_f32 v[52:53], v[66:67], v[52:53]
	v_pk_fma_f32 v[50:51], v[72:73], v[50:51], v[60:61]
	v_mov_b32_e32 v64, v63
	v_pk_mul_f32 v[60:61], v[66:67], v[88:89]
	v_pk_fma_f32 v[54:55], v[72:73], v[84:85], v[54:55]
	v_pk_fma_f32 v[52:53], v[90:91], v[82:83], v[52:53]
	v_pk_fma_f32 v[60:61], v[64:65], v[82:83], v[60:61]
	v_pk_mul_f32 v[52:53], v[54:55], v[52:53]
	v_pk_mul_f32 v[50:51], v[50:51], v[60:61]
	s_and_b64 vcc, exec, s[50:51]
	s_mov_b64 s[0:1], -1
	s_cbranch_vccnz .LBB0_1047
	v_add_u32_e32 v54, v0, v128
	v_ashrrev_i32_e32 v55, 31, v54
	v_bfe_u32 v0, v52, 16, 1
	v_lshlrev_b64 v[54:55], 11, v[54:55]
	v_add3_u32 v0, v52, v0, s33
	v_lshl_add_u64 v[54:55], s[4:5], 0, v[54:55]
	global_store_short_d16_hi v[54:55], v0, off
	v_bfe_u32 v0, v50, 16, 1
	v_add3_u32 v0, v50, v0, s33
	global_store_short_d16_hi v[54:55], v0, off offset:2048
	v_bfe_u32 v0, v53, 16, 1
	v_add_co_u32_e32 v54, vcc, 0x1000, v54
	v_add3_u32 v0, v53, v0, s33
	s_nop 0
	v_addc_co_u32_e32 v55, vcc, 0, v55, vcc
	global_store_short_d16_hi v[54:55], v0, off
	v_bfe_u32 v0, v51, 16, 1
	v_add3_u32 v0, v51, v0, s33
	s_mov_b64 s[0:1], 0
	global_store_short_d16_hi v[54:55], v0, off offset:2048

; __device__ __forceinline__ float bf2f(u16 h) { return __uint_as_float(((unsigned)h) << 16); }
; __device__ __forceinline__ unsigned pack2(float a, float b) { return (unsigned)f2bf(a) | ((unsigned)f2bf(b) << 16); }
; __device__ __forceinline__ void hyena_lat_job(const Params& p, char* smem, int l, int c) {
;     ...
;         int t0 = tb + 32 * mt + 8 * g;
;         float uu[6];
;         {
;           const uint2 mid = *(const uint2*)&u[t0];
;           uu[0] = t0 > 0 ? bf2f(u[t0 - 1]) : 0.f;
;           uu[1] = __uint_as_float(mid.x << 16); uu[2] = __uint_as_float(mid.x & 0xffff0000u);
;           uu[3] = __uint_as_float(mid.y << 16); uu[4] = __uint_as_float(mid.y & 0xffff0000u);
;           uu[5] = t0 + 4 < 8192 ? bf2f(u[t0 + 4]) : 0.f;
;         }
;         const int zi0 = b * 10240 + (t0 >> 5) * 40 + (t0 & 31);
;         const uint2 zo = *(const uint2*)&zs[zi0];
;         float zold4[4] = {__uint_as_float(zo.x << 16), __uint_as_float(zo.x & 0xffff0000u),
;                           __uint_as_float(zo.y << 16), __uint_as_float(zo.y & 0xffff0000u)};
;         float zn4[4];
; #pragma unroll
;         for (int q = 0; q < 4; ++q) {
;           float gate = bb + w0 * uu[q] + w1 * uu[q + 1] + w2 * uu[q + 2];
;           zn4[q] = gate * (scale * acc[mt][g * 4 + q] + zold4[q] * skip);
;         }
;         if (o == 0) {
;           uint2 zw; zw.x = pack2(zn4[0], zn4[1]); zw.y = pack2(zn4[2], zn4[3]);
;           *(uint2*)&zs[zi0] = zw;
;         } else {
; #pragma unroll
;           for (int q = 0; q < 4; ++q) MIX[(size_t)(b * 8192 + t0 + q) * 1024 + 512 + c] = f2bf(zn4[q]);
.LBB0_1049:
	global_load_dwordx2 v[52:53], v[76:77], off offset:64
	s_movk_i32 s0, 0xffe0
	v_add_u32_e32 v0, 32, v78
	v_cmp_lt_i32_e32 vcc, s0, v78
	v_mov_b32_e32 v244, 0
	v_mov_b32_e32 v245, 0
	s_and_saveexec_b64 s[0:1], vcc
	v_lshl_add_u64 v[54:55], v[0:1], 1, v[80:81]
	v_add_co_u32_e32 v54, vcc, -2, v54
	s_nop 1
	v_addc_co_u32_e32 v55, vcc, -1, v55, vcc
	global_load_ushort v244, v[54:55], off
	s_or_b64 exec, exec, s[0:1]
	s_movk_i32 s0, 0x1fdc
	v_cmp_gt_i32_e32 vcc, s0, v78
	s_and_saveexec_b64 s[0:1], vcc
	global_load_ushort v245, v[76:77], off offset:72
	s_or_b64 exec, exec, s[0:1]
	s_waitcnt vmcnt(0) lgkmcnt(0)
	v_lshlrev_b32_e32 v54, 16, v244
	v_lshlrev_b32_e32 v51, 16, v245
	v_ashrrev_i32_e32 v50, 5, v0
	v_mul_lo_u32 v50, v50, s54
	v_add3_u32 v58, v130, v50, v79
	ds_read_b64 v[64:65], v58
	s_waitcnt vmcnt(0) lgkmcnt(0)
	v_and_b32_e32 v62, 0xffff0000, v52
	v_mov_b32_e32 v55, v62
	v_lshlrev_b32_e32 v60, 16, v52
	v_lshlrev_b32_e32 v61, 16, v53
	v_pk_fma_f32 v[54:55], v[70:71], v[54:55], v[74:75]
	v_and_b32_e32 v63, 0xffff0000, v53
	v_mov_b32_e32 v50, v61
	v_lshlrev_b32_e32 v53, 16, v65
	v_lshlrev_b32_e32 v52, 16, v64
	v_and_b32_e32 v65, 0xffff0000, v65
	v_and_b32_e32 v64, 0xffff0000, v64
	v_pk_fma_f32 v[54:55], v[68:69], v[60:61], v[54:55]
	v_pk_fma_f32 v[60:61], v[70:71], v[60:61], v[74:75]
	v_mov_b32_e32 v84, v34
	v_mov_b32_e32 v85, v36
	v_pk_mul_f32 v[52:53], v[66:67], v[52:53]
	v_pk_fma_f32 v[60:61], v[68:69], v[62:63], v[60:61]
	v_mov_b32_e32 v36, v35
	v_pk_mul_f32 v[34:35], v[66:67], v[64:65]
	v_pk_fma_f32 v[54:55], v[72:73], v[62:63], v[54:55]
	v_pk_fma_f32 v[52:53], v[84:85], v[82:83], v[52:53]
	v_pk_fma_f32 v[50:51], v[72:73], v[50:51], v[60:61]
	v_pk_fma_f32 v[34:35], v[36:37], v[82:83], v[34:35]
	v_pk_mul_f32 v[36:37], v[54:55], v[52:53]
	v_pk_mul_f32 v[34:35], v[50:51], v[34:35]
	s_and_b64 vcc, exec, s[50:51]
	s_mov_b64 s[0:1], -1
	s_cbranch_vccnz .LBB0_1055
	v_add_u32_e32 v50, v0, v128
	v_ashrrev_i32_e32 v51, 31, v50
	v_bfe_u32 v0, v36, 16, 1
	v_lshlrev_b64 v[50:51], 11, v[50:51]
	v_add3_u32 v0, v36, v0, s33
	v_lshl_add_u64 v[50:51], s[4:5], 0, v[50:51]
	global_store_short_d16_hi v[50:51], v0, off
	v_bfe_u32 v0, v34, 16, 1
	v_add3_u32 v0, v34, v0, s33
	global_store_short_d16_hi v[50:51], v0, off offset:2048
	v_bfe_u32 v0, v37, 16, 1
	v_add_co_u32_e32 v50, vcc, 0x1000, v50
	v_add3_u32 v0, v37, v0, s33
	s_nop 0
	v_addc_co_u32_e32 v51, vcc, 0, v51, vcc
	global_store_short_d16_hi v[50:51], v0, off
	v_bfe_u32 v0, v35, 16, 1
	v_add3_u32 v0, v35, v0, s33
	s_mov_b64 s[0:1], 0
	global_store_short_d16_hi v[50:51], v0, off offset:2048

; __device__ __forceinline__ float bf2f(u16 h) { return __uint_as_float(((unsigned)h) << 16); }
; __device__ __forceinline__ unsigned pack2(float a, float b) { return (unsigned)f2bf(a) | ((unsigned)f2bf(b) << 16); }
; __device__ __forceinline__ void hyena_lat_job(const Params& p, char* smem, int l, int c) {
;     ...
;         int t0 = tb + 32 * mt + 8 * g;
;         float uu[6];
;         {
;           const uint2 mid = *(const uint2*)&u[t0];
;           uu[0] = t0 > 0 ? bf2f(u[t0 - 1]) : 0.f;
;           uu[1] = __uint_as_float(mid.x << 16); uu[2] = __uint_as_float(mid.x & 0xffff0000u);
;           uu[3] = __uint_as_float(mid.y << 16); uu[4] = __uint_as_float(mid.y & 0xffff0000u);
;           uu[5] = t0 + 4 < 8192 ? bf2f(u[t0 + 4]) : 0.f;
;         }
;         const int zi0 = b * 10240 + (t0 >> 5) * 40 + (t0 & 31);
;         const uint2 zo = *(const uint2*)&zs[zi0];
;         float zold4[4] = {__uint_as_float(zo.x << 16), __uint_as_float(zo.x & 0xffff0000u),
;                           __uint_as_float(zo.y << 16), __uint_as_float(zo.y & 0xffff0000u)};
;         float zn4[4];
; #pragma unroll
;         for (int q = 0; q < 4; ++q) {
;           float gate = bb + w0 * uu[q] + w1 * uu[q + 1] + w2 * uu[q + 2];
;           zn4[q] = gate * (scale * acc[mt][g * 4 + q] + zold4[q] * skip);
;         }
;         if (o == 0) {
;           uint2 zw; zw.x = pack2(zn4[0], zn4[1]); zw.y = pack2(zn4[2], zn4[3]);
;           *(uint2*)&zs[zi0] = zw;
;         } else {
; #pragma unroll
;           for (int q = 0; q < 4; ++q) MIX[(size_t)(b * 8192 + t0 + q) * 1024 + 512 + c] = f2bf(zn4[q]);
.LBB0_1057:
	global_load_dwordx2 v[36:37], v[76:77], off offset:80
	s_movk_i32 s0, 0xffd8
	v_add_u32_e32 v0, 40, v78
	v_cmp_lt_i32_e32 vcc, s0, v78
	v_mov_b32_e32 v244, 0
	v_mov_b32_e32 v245, 0
	s_and_saveexec_b64 s[0:1], vcc
	v_lshl_add_u64 v[50:51], v[0:1], 1, v[80:81]
	v_add_co_u32_e32 v50, vcc, -2, v50
	s_nop 1
	v_addc_co_u32_e32 v51, vcc, -1, v51, vcc
	global_load_ushort v244, v[50:51], off
	s_or_b64 exec, exec, s[0:1]
	s_movk_i32 s0, 0x1fd4
	v_cmp_gt_i32_e32 vcc, s0, v78
	s_and_saveexec_b64 s[0:1], vcc
	global_load_ushort v245, v[76:77], off offset:88
	s_or_b64 exec, exec, s[0:1]
	s_waitcnt vmcnt(0) lgkmcnt(0)
	v_lshlrev_b32_e32 v50, 16, v244
	v_lshlrev_b32_e32 v35, 16, v245
	v_ashrrev_i32_e32 v34, 5, v0
	v_mul_lo_u32 v34, v34, s54
	v_add3_u32 v52, v130, v34, v86
	ds_read_b64 v[60:61], v52
	s_waitcnt vmcnt(0) lgkmcnt(0)
	v_and_b32_e32 v58, 0xffff0000, v36
	v_mov_b32_e32 v51, v58
	v_lshlrev_b32_e32 v54, 16, v36
	v_lshlrev_b32_e32 v55, 16, v37
	v_pk_fma_f32 v[50:51], v[70:71], v[50:51], v[74:75]
	v_and_b32_e32 v59, 0xffff0000, v37
	v_mov_b32_e32 v34, v55
	v_lshlrev_b32_e32 v37, 16, v61
	v_lshlrev_b32_e32 v36, 16, v60
	v_and_b32_e32 v61, 0xffff0000, v61
	v_and_b32_e32 v60, 0xffff0000, v60
	v_pk_fma_f32 v[50:51], v[68:69], v[54:55], v[50:51]
	v_pk_fma_f32 v[54:55], v[70:71], v[54:55], v[74:75]
	v_mov_b32_e32 v62, v38
	v_mov_b32_e32 v63, v40
	v_pk_mul_f32 v[36:37], v[66:67], v[36:37]
	v_pk_fma_f32 v[54:55], v[68:69], v[58:59], v[54:55]
	v_mov_b32_e32 v40, v39
	v_pk_mul_f32 v[38:39], v[66:67], v[60:61]
	v_pk_fma_f32 v[50:51], v[72:73], v[58:59], v[50:51]
	v_pk_fma_f32 v[36:37], v[62:63], v[82:83], v[36:37]
	v_pk_fma_f32 v[34:35], v[72:73], v[34:35], v[54:55]
	v_pk_fma_f32 v[38:39], v[40:41], v[82:83], v[38:39]
	v_pk_mul_f32 v[36:37], v[50:51], v[36:37]
	v_pk_mul_f32 v[34:35], v[34:35], v[38:39]
	s_and_b64 vcc, exec, s[50:51]
	s_mov_b64 s[0:1], -1
	s_cbranch_vccnz .LBB0_1063
	v_add_u32_e32 v38, v0, v128
	v_ashrrev_i32_e32 v39, 31, v38
	v_bfe_u32 v0, v36, 16, 1
	v_lshlrev_b64 v[38:39], 11, v[38:39]
	v_add3_u32 v0, v36, v0, s33
	v_lshl_add_u64 v[38:39], s[4:5], 0, v[38:39]
	global_store_short_d16_hi v[38:39], v0, off
	v_bfe_u32 v0, v34, 16, 1
	v_add3_u32 v0, v34, v0, s33
	global_store_short_d16_hi v[38:39], v0, off offset:2048
	v_bfe_u32 v0, v37, 16, 1
	v_add_co_u32_e32 v38, vcc, 0x1000, v38
	v_add3_u32 v0, v37, v0, s33
	s_nop 0
	v_addc_co_u32_e32 v39, vcc, 0, v39, vcc
	global_store_short_d16_hi v[38:39], v0, off
	v_bfe_u32 v0, v35, 16, 1
	v_add3_u32 v0, v35, v0, s33
	s_mov_b64 s[0:1], 0
	global_store_short_d16_hi v[38:39], v0, off offset:2048

; __device__ __forceinline__ float bf2f(u16 h) { return __uint_as_float(((unsigned)h) << 16); }
; __device__ __forceinline__ unsigned pack2(float a, float b) { return (unsigned)f2bf(a) | ((unsigned)f2bf(b) << 16); }
; __device__ __forceinline__ void hyena_lat_job(const Params& p, char* smem, int l, int c) {
;     ...
;         int t0 = tb + 32 * mt + 8 * g;
;         float uu[6];
;         {
;           const uint2 mid = *(const uint2*)&u[t0];
;           uu[0] = t0 > 0 ? bf2f(u[t0 - 1]) : 0.f;
;           uu[1] = __uint_as_float(mid.x << 16); uu[2] = __uint_as_float(mid.x & 0xffff0000u);
;           uu[3] = __uint_as_float(mid.y << 16); uu[4] = __uint_as_float(mid.y & 0xffff0000u);
;           uu[5] = t0 + 4 < 8192 ? bf2f(u[t0 + 4]) : 0.f;
;         }
;         const int zi0 = b * 10240 + (t0 >> 5) * 40 + (t0 & 31);
;         const uint2 zo = *(const uint2*)&zs[zi0];
;         float zold4[4] = {__uint_as_float(zo.x << 16), __uint_as_float(zo.x & 0xffff0000u),
;                           __uint_as_float(zo.y << 16), __uint_as_float(zo.y & 0xffff0000u)};
;         float zn4[4];
; #pragma unroll
;         for (int q = 0; q < 4; ++q) {
;           float gate = bb + w0 * uu[q] + w1 * uu[q + 1] + w2 * uu[q + 2];
;           zn4[q] = gate * (scale * acc[mt][g * 4 + q] + zold4[q] * skip);
;         }
;         if (o == 0) {
;           uint2 zw; zw.x = pack2(zn4[0], zn4[1]); zw.y = pack2(zn4[2], zn4[3]);
;           *(uint2*)&zs[zi0] = zw;
;         } else {
; #pragma unroll
;           for (int q = 0; q < 4; ++q) MIX[(size_t)(b * 8192 + t0 + q) * 1024 + 512 + c] = f2bf(zn4[q]);
.LBB0_1065:
	global_load_dwordx2 v[36:37], v[76:77], off offset:96
	s_movk_i32 s0, 0xffd0
	v_add_u32_e32 v0, 48, v78
	v_cmp_lt_i32_e32 vcc, s0, v78
	v_mov_b32_e32 v244, 0
	v_mov_b32_e32 v245, 0
	s_and_saveexec_b64 s[0:1], vcc
	v_lshl_add_u64 v[38:39], v[0:1], 1, v[80:81]
	v_add_co_u32_e32 v38, vcc, -2, v38
	s_nop 1
	v_addc_co_u32_e32 v39, vcc, -1, v39, vcc
	global_load_ushort v244, v[38:39], off
	s_or_b64 exec, exec, s[0:1]
	s_movk_i32 s0, 0x1fcc
	v_cmp_gt_i32_e32 vcc, s0, v78
	s_and_saveexec_b64 s[0:1], vcc
	global_load_ushort v245, v[76:77], off offset:104
	s_or_b64 exec, exec, s[0:1]
	s_waitcnt vmcnt(0) lgkmcnt(0)
	v_lshlrev_b32_e32 v38, 16, v244
	v_lshlrev_b32_e32 v35, 16, v245
	v_ashrrev_i32_e32 v34, 5, v0
	v_mul_lo_u32 v34, v34, s54
	v_add3_u32 v40, v130, v34, v56
	ds_read_b64 v[54:55], v40
	s_waitcnt vmcnt(0) lgkmcnt(0)
	v_and_b32_e32 v52, 0xffff0000, v36
	v_mov_b32_e32 v39, v52
	v_lshlrev_b32_e32 v50, 16, v36
	v_lshlrev_b32_e32 v51, 16, v37
	v_pk_fma_f32 v[38:39], v[70:71], v[38:39], v[74:75]
	v_and_b32_e32 v53, 0xffff0000, v37
	v_mov_b32_e32 v34, v51
	v_lshlrev_b32_e32 v37, 16, v55
	v_lshlrev_b32_e32 v36, 16, v54
	v_and_b32_e32 v55, 0xffff0000, v55
	v_and_b32_e32 v54, 0xffff0000, v54
	v_pk_fma_f32 v[38:39], v[68:69], v[50:51], v[38:39]
	v_pk_fma_f32 v[50:51], v[70:71], v[50:51], v[74:75]
	v_mov_b32_e32 v58, v42
	v_mov_b32_e32 v59, v44
	v_pk_mul_f32 v[36:37], v[66:67], v[36:37]
	v_pk_fma_f32 v[50:51], v[68:69], v[52:53], v[50:51]
	v_mov_b32_e32 v44, v43
	v_pk_mul_f32 v[42:43], v[66:67], v[54:55]
	v_pk_fma_f32 v[38:39], v[72:73], v[52:53], v[38:39]
	v_pk_fma_f32 v[36:37], v[58:59], v[82:83], v[36:37]
	v_pk_fma_f32 v[34:35], v[72:73], v[34:35], v[50:51]
	v_pk_fma_f32 v[42:43], v[44:45], v[82:83], v[42:43]
	v_pk_mul_f32 v[36:37], v[38:39], v[36:37]
	v_pk_mul_f32 v[34:35], v[34:35], v[42:43]
	s_and_b64 vcc, exec, s[50:51]
	s_mov_b64 s[0:1], -1
	s_cbranch_vccnz .LBB0_1071
	v_add_u32_e32 v38, v0, v128
	v_ashrrev_i32_e32 v39, 31, v38
	v_bfe_u32 v0, v36, 16, 1
	v_lshlrev_b64 v[38:39], 11, v[38:39]
	v_add3_u32 v0, v36, v0, s33
	v_lshl_add_u64 v[38:39], s[4:5], 0, v[38:39]
	global_store_short_d16_hi v[38:39], v0, off
	v_bfe_u32 v0, v34, 16, 1
	v_add3_u32 v0, v34, v0, s33
	global_store_short_d16_hi v[38:39], v0, off offset:2048
	v_bfe_u32 v0, v37, 16, 1
	v_add_co_u32_e32 v38, vcc, 0x1000, v38
	v_add3_u32 v0, v37, v0, s33
	s_nop 0
	v_addc_co_u32_e32 v39, vcc, 0, v39, vcc
	global_store_short_d16_hi v[38:39], v0, off
	v_bfe_u32 v0, v35, 16, 1
	v_add3_u32 v0, v35, v0, s33
	s_mov_b64 s[0:1], 0
	global_store_short_d16_hi v[38:39], v0, off offset:2048

; __device__ __forceinline__ float bf2f(u16 h) { return __uint_as_float(((unsigned)h) << 16); }
; __device__ __forceinline__ unsigned pack2(float a, float b) { return (unsigned)f2bf(a) | ((unsigned)f2bf(b) << 16); }
; __device__ __forceinline__ void hyena_lat_job(const Params& p, char* smem, int l, int c) {
;     ...
;         int t0 = tb + 32 * mt + 8 * g;
;         float uu[6];
;         {
;           const uint2 mid = *(const uint2*)&u[t0];
;           uu[0] = t0 > 0 ? bf2f(u[t0 - 1]) : 0.f;
;           uu[1] = __uint_as_float(mid.x << 16); uu[2] = __uint_as_float(mid.x & 0xffff0000u);
;           uu[3] = __uint_as_float(mid.y << 16); uu[4] = __uint_as_float(mid.y & 0xffff0000u);
;           uu[5] = t0 + 4 < 8192 ? bf2f(u[t0 + 4]) : 0.f;
;         }
;         const int zi0 = b * 10240 + (t0 >> 5) * 40 + (t0 & 31);
;         const uint2 zo = *(const uint2*)&zs[zi0];
;         float zold4[4] = {__uint_as_float(zo.x << 16), __uint_as_float(zo.x & 0xffff0000u),
;                           __uint_as_float(zo.y << 16), __uint_as_float(zo.y & 0xffff0000u)};
;         float zn4[4];
; #pragma unroll
;         for (int q = 0; q < 4; ++q) {
;           float gate = bb + w0 * uu[q] + w1 * uu[q + 1] + w2 * uu[q + 2];
;           zn4[q] = gate * (scale * acc[mt][g * 4 + q] + zold4[q] * skip);
;         }
;         if (o == 0) {
;           uint2 zw; zw.x = pack2(zn4[0], zn4[1]); zw.y = pack2(zn4[2], zn4[3]);
;           *(uint2*)&zs[zi0] = zw;
;         } else {
; #pragma unroll
;           for (int q = 0; q < 4; ++q) MIX[(size_t)(b * 8192 + t0 + q) * 1024 + 512 + c] = f2bf(zn4[q]);
.LBB0_1073:
	global_load_dwordx2 v[36:37], v[76:77], off offset:112
	s_movk_i32 s0, 0xffc8
	v_add_u32_e32 v0, 56, v78
	v_cmp_lt_i32_e32 vcc, s0, v78
	v_mov_b32_e32 v244, 0
	v_mov_b32_e32 v245, 0
	s_and_saveexec_b64 s[0:1], vcc
	v_lshl_add_u64 v[38:39], v[0:1], 1, v[80:81]
	v_add_co_u32_e32 v38, vcc, -2, v38
	s_nop 1
	v_addc_co_u32_e32 v39, vcc, -1, v39, vcc
	global_load_ushort v244, v[38:39], off
	s_or_b64 exec, exec, s[0:1]
	s_movk_i32 s0, 0x1fc4
	v_cmp_gt_i32_e32 vcc, s0, v78
	s_and_saveexec_b64 s[0:1], vcc
	global_load_ushort v245, v[76:77], off offset:120
	s_or_b64 exec, exec, s[0:1]
	s_waitcnt vmcnt(0) lgkmcnt(0)
	v_lshlrev_b32_e32 v38, 16, v244
	v_lshlrev_b32_e32 v35, 16, v245
	v_ashrrev_i32_e32 v34, 5, v0
	v_mul_lo_u32 v34, v34, s54
	v_add3_u32 v40, v130, v34, v57
	ds_read_b64 v[50:51], v40
	s_waitcnt vmcnt(0) lgkmcnt(0)
	v_and_b32_e32 v44, 0xffff0000, v36
	v_mov_b32_e32 v39, v44
	v_lshlrev_b32_e32 v42, 16, v36
	v_lshlrev_b32_e32 v43, 16, v37
	v_pk_fma_f32 v[38:39], v[70:71], v[38:39], v[74:75]
	v_and_b32_e32 v45, 0xffff0000, v37
	v_mov_b32_e32 v34, v43
	v_pk_fma_f32 v[38:39], v[68:69], v[42:43], v[38:39]
	v_pk_fma_f32 v[42:43], v[70:71], v[42:43], v[74:75]
	v_lshlrev_b32_e32 v37, 16, v51
	v_lshlrev_b32_e32 v36, 16, v50
	v_and_b32_e32 v51, 0xffff0000, v51
	v_and_b32_e32 v50, 0xffff0000, v50
	v_pk_fma_f32 v[42:43], v[68:69], v[44:45], v[42:43]
	v_mov_b32_e32 v52, v46
	v_mov_b32_e32 v53, v48
	v_pk_mul_f32 v[36:37], v[66:67], v[36:37]
	v_pk_fma_f32 v[34:35], v[72:73], v[34:35], v[42:43]
	v_mov_b32_e32 v48, v47
	v_pk_mul_f32 v[42:43], v[66:67], v[50:51]
	v_pk_fma_f32 v[38:39], v[72:73], v[44:45], v[38:39]
	v_pk_fma_f32 v[36:37], v[52:53], v[82:83], v[36:37]
	v_pk_fma_f32 v[42:43], v[48:49], v[82:83], v[42:43]
	v_pk_mul_f32 v[36:37], v[38:39], v[36:37]
	v_pk_mul_f32 v[34:35], v[34:35], v[42:43]
	s_and_b64 vcc, exec, s[50:51]
	s_mov_b64 s[0:1], -1
	s_cbranch_vccnz .LBB0_1079
	v_add_u32_e32 v38, v0, v128
	v_ashrrev_i32_e32 v39, 31, v38
	v_bfe_u32 v0, v36, 16, 1
	v_lshlrev_b64 v[38:39], 11, v[38:39]
	v_add3_u32 v0, v36, v0, s33
	v_lshl_add_u64 v[38:39], s[4:5], 0, v[38:39]
	global_store_short_d16_hi v[38:39], v0, off
	v_bfe_u32 v0, v34, 16, 1
	v_add3_u32 v0, v34, v0, s33
	global_store_short_d16_hi v[38:39], v0, off offset:2048
	v_bfe_u32 v0, v37, 16, 1
	v_add_co_u32_e32 v38, vcc, 0x1000, v38
	v_add3_u32 v0, v37, v0, s33
	s_nop 0
	v_addc_co_u32_e32 v39, vcc, 0, v39, vcc
	global_store_short_d16_hi v[38:39], v0, off
	v_bfe_u32 v0, v35, 16, 1
	v_add3_u32 v0, v35, v0, s33
	s_mov_b64 s[0:1], 0
	global_store_short_d16_hi v[38:39], v0, off offset:2048

; __device__ __forceinline__ float bf2f(u16 h) { return __uint_as_float(((unsigned)h) << 16); }
; __device__ __forceinline__ unsigned pack2(float a, float b) { return (unsigned)f2bf(a) | ((unsigned)f2bf(b) << 16); }
; __device__ __forceinline__ void hyena_lat_job(const Params& p, char* smem, int l, int c) {
;     ...
;         int t0 = tb + 32 * mt + 8 * g;
;         float uu[6];
;         {
;           const uint2 mid = *(const uint2*)&u[t0];
;           uu[0] = t0 > 0 ? bf2f(u[t0 - 1]) : 0.f;
;           uu[1] = __uint_as_float(mid.x << 16); uu[2] = __uint_as_float(mid.x & 0xffff0000u);
;           uu[3] = __uint_as_float(mid.y << 16); uu[4] = __uint_as_float(mid.y & 0xffff0000u);
;           uu[5] = t0 + 4 < 8192 ? bf2f(u[t0 + 4]) : 0.f;
;         }
;         const int zi0 = b * 10240 + (t0 >> 5) * 40 + (t0 & 31);
;         const uint2 zo = *(const uint2*)&zs[zi0];
;         float zold4[4] = {__uint_as_float(zo.x << 16), __uint_as_float(zo.x & 0xffff0000u),
;                           __uint_as_float(zo.y << 16), __uint_as_float(zo.y & 0xffff0000u)};
;         float zn4[4];
; #pragma unroll
;         for (int q = 0; q < 4; ++q) {
;           float gate = bb + w0 * uu[q] + w1 * uu[q + 1] + w2 * uu[q + 2];
;           zn4[q] = gate * (scale * acc[mt][g * 4 + q] + zold4[q] * skip);
;         }
;         if (o == 0) {
;           uint2 zw; zw.x = pack2(zn4[0], zn4[1]); zw.y = pack2(zn4[2], zn4[3]);
;           *(uint2*)&zs[zi0] = zw;
;         } else {
; #pragma unroll
;           for (int q = 0; q < 4; ++q) MIX[(size_t)(b * 8192 + t0 + q) * 1024 + 512 + c] = f2bf(zn4[q]);
.LBB0_1089:
	global_load_dwordx2 v[20:21], v[76:77], off offset:144
	s_movk_i32 s0, 0xffb8
	v_add_u32_e32 v0, 0x48, v78
	v_cmp_lt_i32_e32 vcc, s0, v78
	v_mov_b32_e32 v244, 0
	v_mov_b32_e32 v245, 0
	s_and_saveexec_b64 s[0:1], vcc
	v_lshl_add_u64 v[34:35], v[0:1], 1, v[80:81]
	v_add_co_u32_e32 v34, vcc, -2, v34
	s_nop 1
	v_addc_co_u32_e32 v35, vcc, -1, v35, vcc
	global_load_ushort v244, v[34:35], off
	s_or_b64 exec, exec, s[0:1]
	s_movk_i32 s0, 0x1fb4
	v_cmp_gt_i32_e32 vcc, s0, v78
	s_and_saveexec_b64 s[0:1], vcc
	global_load_ushort v245, v[76:77], off offset:152
	s_or_b64 exec, exec, s[0:1]
	s_waitcnt vmcnt(0) lgkmcnt(0)
	v_lshlrev_b32_e32 v34, 16, v244
	v_lshlrev_b32_e32 v19, 16, v245
	v_ashrrev_i32_e32 v18, 5, v0
	v_mul_lo_u32 v18, v18, s54
	v_add3_u32 v36, v130, v18, v86
	ds_read_b64 v[42:43], v36
	s_waitcnt vmcnt(0) lgkmcnt(0)
	v_and_b32_e32 v40, 0xffff0000, v20
	v_mov_b32_e32 v35, v40
	v_lshlrev_b32_e32 v38, 16, v20
	v_lshlrev_b32_e32 v39, 16, v21
	v_pk_fma_f32 v[34:35], v[70:71], v[34:35], v[74:75]
	v_and_b32_e32 v41, 0xffff0000, v21
	v_mov_b32_e32 v18, v39
	v_lshlrev_b32_e32 v21, 16, v43
	v_lshlrev_b32_e32 v20, 16, v42
	v_and_b32_e32 v43, 0xffff0000, v43
	v_and_b32_e32 v42, 0xffff0000, v42
	v_pk_fma_f32 v[34:35], v[68:69], v[38:39], v[34:35]
	v_pk_fma_f32 v[38:39], v[70:71], v[38:39], v[74:75]
	v_mov_b32_e32 v44, v22
	v_mov_b32_e32 v45, v24
	v_pk_mul_f32 v[20:21], v[66:67], v[20:21]
	v_pk_fma_f32 v[38:39], v[68:69], v[40:41], v[38:39]
	v_mov_b32_e32 v24, v23
	v_pk_mul_f32 v[22:23], v[66:67], v[42:43]
	v_pk_fma_f32 v[34:35], v[72:73], v[40:41], v[34:35]
	v_pk_fma_f32 v[20:21], v[44:45], v[82:83], v[20:21]
	v_pk_fma_f32 v[18:19], v[72:73], v[18:19], v[38:39]
	v_pk_fma_f32 v[22:23], v[24:25], v[82:83], v[22:23]
	v_pk_mul_f32 v[20:21], v[34:35], v[20:21]
	v_pk_mul_f32 v[18:19], v[18:19], v[22:23]
	s_and_b64 vcc, exec, s[50:51]
	s_mov_b64 s[0:1], -1
	s_cbranch_vccnz .LBB0_1095
	v_add_u32_e32 v22, v0, v128
	v_ashrrev_i32_e32 v23, 31, v22
	v_bfe_u32 v0, v20, 16, 1
	v_lshlrev_b64 v[22:23], 11, v[22:23]
	v_add3_u32 v0, v20, v0, s33
	v_lshl_add_u64 v[22:23], s[4:5], 0, v[22:23]
	global_store_short_d16_hi v[22:23], v0, off
	v_bfe_u32 v0, v18, 16, 1
	v_add3_u32 v0, v18, v0, s33
	global_store_short_d16_hi v[22:23], v0, off offset:2048
	v_bfe_u32 v0, v21, 16, 1
	v_add_co_u32_e32 v22, vcc, 0x1000, v22
	v_add3_u32 v0, v21, v0, s33
	s_nop 0
	v_addc_co_u32_e32 v23, vcc, 0, v23, vcc
	global_store_short_d16_hi v[22:23], v0, off
	v_bfe_u32 v0, v19, 16, 1
	v_add3_u32 v0, v19, v0, s33
	s_mov_b64 s[0:1], 0
	global_store_short_d16_hi v[22:23], v0, off offset:2048

; __device__ __forceinline__ float bf2f(u16 h) { return __uint_as_float(((unsigned)h) << 16); }
; __device__ __forceinline__ unsigned pack2(float a, float b) { return (unsigned)f2bf(a) | ((unsigned)f2bf(b) << 16); }
; __device__ __forceinline__ void hyena_lat_job(const Params& p, char* smem, int l, int c) {
;     ...
;         int t0 = tb + 32 * mt + 8 * g;
;         float uu[6];
;         {
;           const uint2 mid = *(const uint2*)&u[t0];
;           uu[0] = t0 > 0 ? bf2f(u[t0 - 1]) : 0.f;
;           uu[1] = __uint_as_float(mid.x << 16); uu[2] = __uint_as_float(mid.x & 0xffff0000u);
;           uu[3] = __uint_as_float(mid.y << 16); uu[4] = __uint_as_float(mid.y & 0xffff0000u);
;           uu[5] = t0 + 4 < 8192 ? bf2f(u[t0 + 4]) : 0.f;
;         }
;         const int zi0 = b * 10240 + (t0 >> 5) * 40 + (t0 & 31);
;         const uint2 zo = *(const uint2*)&zs[zi0];
;         float zold4[4] = {__uint_as_float(zo.x << 16), __uint_as_float(zo.x & 0xffff0000u),
;                           __uint_as_float(zo.y << 16), __uint_as_float(zo.y & 0xffff0000u)};
;         float zn4[4];
; #pragma unroll
;         for (int q = 0; q < 4; ++q) {
;           float gate = bb + w0 * uu[q] + w1 * uu[q + 1] + w2 * uu[q + 2];
;           zn4[q] = gate * (scale * acc[mt][g * 4 + q] + zold4[q] * skip);
;         }
;         if (o == 0) {
;           uint2 zw; zw.x = pack2(zn4[0], zn4[1]); zw.y = pack2(zn4[2], zn4[3]);
;           *(uint2*)&zs[zi0] = zw;
;         } else {
; #pragma unroll
;           for (int q = 0; q < 4; ++q) MIX[(size_t)(b * 8192 + t0 + q) * 1024 + 512 + c] = f2bf(zn4[q]);
.LBB0_1097:
	global_load_dwordx2 v[20:21], v[76:77], off offset:160
	s_movk_i32 s0, 0xffb0
	v_add_u32_e32 v0, 0x50, v78
	v_cmp_lt_i32_e32 vcc, s0, v78
	v_mov_b32_e32 v244, 0
	v_mov_b32_e32 v245, 0
	s_and_saveexec_b64 s[0:1], vcc
	v_lshl_add_u64 v[22:23], v[0:1], 1, v[80:81]
	v_add_co_u32_e32 v22, vcc, -2, v22
	s_nop 1
	v_addc_co_u32_e32 v23, vcc, -1, v23, vcc
	global_load_ushort v244, v[22:23], off
	s_or_b64 exec, exec, s[0:1]
	s_movk_i32 s0, 0x1fac
	v_cmp_gt_i32_e32 vcc, s0, v78
	s_and_saveexec_b64 s[0:1], vcc
	global_load_ushort v245, v[76:77], off offset:168
	s_or_b64 exec, exec, s[0:1]
	s_waitcnt vmcnt(0) lgkmcnt(0)
	v_lshlrev_b32_e32 v22, 16, v244
	v_lshlrev_b32_e32 v19, 16, v245
	v_ashrrev_i32_e32 v18, 5, v0
	v_mul_lo_u32 v18, v18, s54
	v_add3_u32 v24, v130, v18, v56
	ds_read_b64 v[38:39], v24
	s_waitcnt vmcnt(0) lgkmcnt(0)
	v_and_b32_e32 v36, 0xffff0000, v20
	v_mov_b32_e32 v23, v36
	v_lshlrev_b32_e32 v34, 16, v20
	v_lshlrev_b32_e32 v35, 16, v21
	v_pk_fma_f32 v[22:23], v[70:71], v[22:23], v[74:75]
	v_and_b32_e32 v37, 0xffff0000, v21
	v_mov_b32_e32 v18, v35
	v_lshlrev_b32_e32 v21, 16, v39
	v_lshlrev_b32_e32 v20, 16, v38
	v_and_b32_e32 v39, 0xffff0000, v39
	v_and_b32_e32 v38, 0xffff0000, v38
	v_pk_fma_f32 v[22:23], v[68:69], v[34:35], v[22:23]
	v_pk_fma_f32 v[34:35], v[70:71], v[34:35], v[74:75]
	v_mov_b32_e32 v40, v26
	v_mov_b32_e32 v41, v28
	v_pk_mul_f32 v[20:21], v[66:67], v[20:21]
	v_pk_fma_f32 v[34:35], v[68:69], v[36:37], v[34:35]
	v_mov_b32_e32 v28, v27
	v_pk_mul_f32 v[26:27], v[66:67], v[38:39]
	v_pk_fma_f32 v[22:23], v[72:73], v[36:37], v[22:23]
	v_pk_fma_f32 v[20:21], v[40:41], v[82:83], v[20:21]
	v_pk_fma_f32 v[18:19], v[72:73], v[18:19], v[34:35]
	v_pk_fma_f32 v[26:27], v[28:29], v[82:83], v[26:27]
	v_pk_mul_f32 v[20:21], v[22:23], v[20:21]
	v_pk_mul_f32 v[18:19], v[18:19], v[26:27]
	s_and_b64 vcc, exec, s[50:51]
	s_mov_b64 s[0:1], -1
	s_cbranch_vccnz .LBB0_1103
	v_add_u32_e32 v22, v0, v128
	v_ashrrev_i32_e32 v23, 31, v22
	v_bfe_u32 v0, v20, 16, 1
	v_lshlrev_b64 v[22:23], 11, v[22:23]
	v_add3_u32 v0, v20, v0, s33
	v_lshl_add_u64 v[22:23], s[4:5], 0, v[22:23]
	global_store_short_d16_hi v[22:23], v0, off
	v_bfe_u32 v0, v18, 16, 1
	v_add3_u32 v0, v18, v0, s33
	global_store_short_d16_hi v[22:23], v0, off offset:2048
	v_bfe_u32 v0, v21, 16, 1
	v_add_co_u32_e32 v22, vcc, 0x1000, v22
	v_add3_u32 v0, v21, v0, s33
	s_nop 0
	v_addc_co_u32_e32 v23, vcc, 0, v23, vcc
	global_store_short_d16_hi v[22:23], v0, off
	v_bfe_u32 v0, v19, 16, 1
	v_add3_u32 v0, v19, v0, s33
	s_mov_b64 s[0:1], 0
	global_store_short_d16_hi v[22:23], v0, off offset:2048

; __device__ __forceinline__ float bf2f(u16 h) { return __uint_as_float(((unsigned)h) << 16); }
; __device__ __forceinline__ unsigned pack2(float a, float b) { return (unsigned)f2bf(a) | ((unsigned)f2bf(b) << 16); }
; __device__ __forceinline__ void hyena_lat_job(const Params& p, char* smem, int l, int c) {
;     ...
;         int t0 = tb + 32 * mt + 8 * g;
;         float uu[6];
;         {
;           const uint2 mid = *(const uint2*)&u[t0];
;           uu[0] = t0 > 0 ? bf2f(u[t0 - 1]) : 0.f;
;           uu[1] = __uint_as_float(mid.x << 16); uu[2] = __uint_as_float(mid.x & 0xffff0000u);
;           uu[3] = __uint_as_float(mid.y << 16); uu[4] = __uint_as_float(mid.y & 0xffff0000u);
;           uu[5] = t0 + 4 < 8192 ? bf2f(u[t0 + 4]) : 0.f;
;         }
;         const int zi0 = b * 10240 + (t0 >> 5) * 40 + (t0 & 31);
;         const uint2 zo = *(const uint2*)&zs[zi0];
;         float zold4[4] = {__uint_as_float(zo.x << 16), __uint_as_float(zo.x & 0xffff0000u),
;                           __uint_as_float(zo.y << 16), __uint_as_float(zo.y & 0xffff0000u)};
;         float zn4[4];
; #pragma unroll
;         for (int q = 0; q < 4; ++q) {
;           float gate = bb + w0 * uu[q] + w1 * uu[q + 1] + w2 * uu[q + 2];
;           zn4[q] = gate * (scale * acc[mt][g * 4 + q] + zold4[q] * skip);
;         }
;         if (o == 0) {
;           uint2 zw; zw.x = pack2(zn4[0], zn4[1]); zw.y = pack2(zn4[2], zn4[3]);
;           *(uint2*)&zs[zi0] = zw;
;         } else {
; #pragma unroll
;           for (int q = 0; q < 4; ++q) MIX[(size_t)(b * 8192 + t0 + q) * 1024 + 512 + c] = f2bf(zn4[q]);
.LBB0_1105:
	global_load_dwordx2 v[20:21], v[76:77], off offset:176
	s_movk_i32 s0, 0xffa8
	v_add_u32_e32 v0, 0x58, v78
	v_cmp_lt_i32_e32 vcc, s0, v78
	v_mov_b32_e32 v244, 0
	v_mov_b32_e32 v245, 0
	s_and_saveexec_b64 s[0:1], vcc
	v_lshl_add_u64 v[22:23], v[0:1], 1, v[80:81]
	v_add_co_u32_e32 v22, vcc, -2, v22
	s_nop 1
	v_addc_co_u32_e32 v23, vcc, -1, v23, vcc
	global_load_ushort v244, v[22:23], off
	s_or_b64 exec, exec, s[0:1]
	s_movk_i32 s0, 0x1fa4
	v_cmp_gt_i32_e32 vcc, s0, v78
	s_and_saveexec_b64 s[0:1], vcc
	global_load_ushort v245, v[76:77], off offset:184
	s_or_b64 exec, exec, s[0:1]
	s_waitcnt vmcnt(0) lgkmcnt(0)
	v_lshlrev_b32_e32 v22, 16, v244
	v_lshlrev_b32_e32 v19, 16, v245
	v_ashrrev_i32_e32 v18, 5, v0
	v_mul_lo_u32 v18, v18, s54
	v_add3_u32 v24, v130, v18, v57
	ds_read_b64 v[34:35], v24
	s_waitcnt vmcnt(0) lgkmcnt(0)
	v_and_b32_e32 v28, 0xffff0000, v20
	v_mov_b32_e32 v23, v28
	v_lshlrev_b32_e32 v26, 16, v20
	v_lshlrev_b32_e32 v27, 16, v21
	v_pk_fma_f32 v[22:23], v[70:71], v[22:23], v[74:75]
	v_and_b32_e32 v29, 0xffff0000, v21
	v_mov_b32_e32 v18, v27
	v_pk_fma_f32 v[22:23], v[68:69], v[26:27], v[22:23]
	v_pk_fma_f32 v[26:27], v[70:71], v[26:27], v[74:75]
	v_lshlrev_b32_e32 v21, 16, v35
	v_lshlrev_b32_e32 v20, 16, v34
	v_and_b32_e32 v35, 0xffff0000, v35
	v_and_b32_e32 v34, 0xffff0000, v34
	v_pk_fma_f32 v[26:27], v[68:69], v[28:29], v[26:27]
	v_mov_b32_e32 v36, v30
	v_mov_b32_e32 v37, v32
	v_pk_mul_f32 v[20:21], v[66:67], v[20:21]
	v_pk_fma_f32 v[18:19], v[72:73], v[18:19], v[26:27]
	v_mov_b32_e32 v32, v31
	v_pk_mul_f32 v[26:27], v[66:67], v[34:35]
	v_pk_fma_f32 v[22:23], v[72:73], v[28:29], v[22:23]
	v_pk_fma_f32 v[20:21], v[36:37], v[82:83], v[20:21]
	v_pk_fma_f32 v[26:27], v[32:33], v[82:83], v[26:27]
	v_pk_mul_f32 v[20:21], v[22:23], v[20:21]
	v_pk_mul_f32 v[18:19], v[18:19], v[26:27]
	s_and_b64 vcc, exec, s[50:51]
	s_mov_b64 s[0:1], -1
	s_cbranch_vccnz .LBB0_1111
	v_add_u32_e32 v22, v0, v128
	v_ashrrev_i32_e32 v23, 31, v22
	v_bfe_u32 v0, v20, 16, 1
	v_lshlrev_b64 v[22:23], 11, v[22:23]
	v_add3_u32 v0, v20, v0, s33
	v_lshl_add_u64 v[22:23], s[4:5], 0, v[22:23]
	global_store_short_d16_hi v[22:23], v0, off
	v_bfe_u32 v0, v18, 16, 1
	v_add3_u32 v0, v18, v0, s33
	global_store_short_d16_hi v[22:23], v0, off offset:2048
	v_bfe_u32 v0, v21, 16, 1
	v_add_co_u32_e32 v22, vcc, 0x1000, v22
	v_add3_u32 v0, v21, v0, s33
	s_nop 0
	v_addc_co_u32_e32 v23, vcc, 0, v23, vcc
	global_store_short_d16_hi v[22:23], v0, off
	v_bfe_u32 v0, v19, 16, 1
	v_add3_u32 v0, v19, v0, s33
	s_mov_b64 s[0:1], 0
	global_store_short_d16_hi v[22:23], v0, off offset:2048

; __device__ __forceinline__ float bf2f(u16 h) { return __uint_as_float(((unsigned)h) << 16); }
; __device__ __forceinline__ unsigned pack2(float a, float b) { return (unsigned)f2bf(a) | ((unsigned)f2bf(b) << 16); }
; __device__ __forceinline__ void hyena_lat_job(const Params& p, char* smem, int l, int c) {
;     ...
;         int t0 = tb + 32 * mt + 8 * g;
;         float uu[6];
;         {
;           const uint2 mid = *(const uint2*)&u[t0];
;           uu[0] = t0 > 0 ? bf2f(u[t0 - 1]) : 0.f;
;           uu[1] = __uint_as_float(mid.x << 16); uu[2] = __uint_as_float(mid.x & 0xffff0000u);
;           uu[3] = __uint_as_float(mid.y << 16); uu[4] = __uint_as_float(mid.y & 0xffff0000u);
;           uu[5] = t0 + 4 < 8192 ? bf2f(u[t0 + 4]) : 0.f;
;         }
;         const int zi0 = b * 10240 + (t0 >> 5) * 40 + (t0 & 31);
;         const uint2 zo = *(const uint2*)&zs[zi0];
;         float zold4[4] = {__uint_as_float(zo.x << 16), __uint_as_float(zo.x & 0xffff0000u),
;                           __uint_as_float(zo.y << 16), __uint_as_float(zo.y & 0xffff0000u)};
;         float zn4[4];
; #pragma unroll
;         for (int q = 0; q < 4; ++q) {
;           float gate = bb + w0 * uu[q] + w1 * uu[q + 1] + w2 * uu[q + 2];
;           zn4[q] = gate * (scale * acc[mt][g * 4 + q] + zold4[q] * skip);
;         }
;         if (o == 0) {
;           uint2 zw; zw.x = pack2(zn4[0], zn4[1]); zw.y = pack2(zn4[2], zn4[3]);
;           *(uint2*)&zs[zi0] = zw;
;         } else {
; #pragma unroll
;           for (int q = 0; q < 4; ++q) MIX[(size_t)(b * 8192 + t0 + q) * 1024 + 512 + c] = f2bf(zn4[q]);
.LBB0_1113:
	global_load_dwordx2 v[20:21], v[76:77], off offset:192
	s_movk_i32 s0, 0xffa0
	v_add_u32_e32 v0, 0x60, v78
	v_cmp_lt_i32_e32 vcc, s0, v78
	v_mov_b32_e32 v244, 0
	v_mov_b32_e32 v245, 0
	s_and_saveexec_b64 s[0:1], vcc
	v_lshl_add_u64 v[22:23], v[0:1], 1, v[80:81]
	v_add_co_u32_e32 v22, vcc, -2, v22
	s_nop 1
	v_addc_co_u32_e32 v23, vcc, -1, v23, vcc
	global_load_ushort v244, v[22:23], off
	s_or_b64 exec, exec, s[0:1]
	s_movk_i32 s0, 0x1f9c
	v_cmp_gt_i32_e32 vcc, s0, v78
	s_and_saveexec_b64 s[0:1], vcc
	global_load_ushort v245, v[76:77], off offset:200
	s_or_b64 exec, exec, s[0:1]
	s_waitcnt vmcnt(0) lgkmcnt(0)
	v_lshlrev_b32_e32 v22, 16, v244
	v_lshlrev_b32_e32 v19, 16, v245
	v_ashrrev_i32_e32 v18, 5, v0
	v_mul_lo_u32 v18, v18, s54
	v_add3_u32 v24, v130, v18, v79
	ds_read_b64 v[30:31], v24
	s_waitcnt vmcnt(0) lgkmcnt(0)
	v_and_b32_e32 v28, 0xffff0000, v20
	v_mov_b32_e32 v23, v28
	v_lshlrev_b32_e32 v26, 16, v20
	v_lshlrev_b32_e32 v27, 16, v21
	v_pk_fma_f32 v[22:23], v[70:71], v[22:23], v[74:75]
	v_and_b32_e32 v29, 0xffff0000, v21
	v_mov_b32_e32 v18, v27
	v_lshlrev_b32_e32 v21, 16, v31
	v_lshlrev_b32_e32 v20, 16, v30
	v_and_b32_e32 v31, 0xffff0000, v31
	v_and_b32_e32 v30, 0xffff0000, v30
	v_pk_fma_f32 v[22:23], v[68:69], v[26:27], v[22:23]
	v_pk_fma_f32 v[26:27], v[70:71], v[26:27], v[74:75]
	v_mov_b32_e32 v32, v2
	v_mov_b32_e32 v33, v4
	v_pk_mul_f32 v[20:21], v[66:67], v[20:21]
	v_pk_fma_f32 v[26:27], v[68:69], v[28:29], v[26:27]
	v_mov_b32_e32 v4, v3
	v_pk_mul_f32 v[2:3], v[66:67], v[30:31]
	v_pk_fma_f32 v[22:23], v[72:73], v[28:29], v[22:23]
	v_pk_fma_f32 v[20:21], v[32:33], v[82:83], v[20:21]
	v_pk_fma_f32 v[18:19], v[72:73], v[18:19], v[26:27]
	v_pk_fma_f32 v[2:3], v[4:5], v[82:83], v[2:3]
	v_pk_mul_f32 v[4:5], v[22:23], v[20:21]
	v_pk_mul_f32 v[2:3], v[18:19], v[2:3]
	s_and_b64 vcc, exec, s[50:51]
	s_mov_b64 s[0:1], -1
	s_cbranch_vccnz .LBB0_1119
	v_add_u32_e32 v18, v0, v128
	v_ashrrev_i32_e32 v19, 31, v18
	v_bfe_u32 v0, v4, 16, 1
	v_lshlrev_b64 v[18:19], 11, v[18:19]
	v_add3_u32 v0, v4, v0, s33
	v_lshl_add_u64 v[18:19], s[4:5], 0, v[18:19]
	global_store_short_d16_hi v[18:19], v0, off
	v_bfe_u32 v0, v2, 16, 1
	v_add3_u32 v0, v2, v0, s33
	global_store_short_d16_hi v[18:19], v0, off offset:2048
	v_bfe_u32 v0, v5, 16, 1
	v_add_co_u32_e32 v18, vcc, 0x1000, v18
	v_add3_u32 v0, v5, v0, s33
	s_nop 0
	v_addc_co_u32_e32 v19, vcc, 0, v19, vcc
	global_store_short_d16_hi v[18:19], v0, off
	v_bfe_u32 v0, v3, 16, 1
	v_add3_u32 v0, v3, v0, s33
	s_mov_b64 s[0:1], 0
	global_store_short_d16_hi v[18:19], v0, off offset:2048

; __device__ __forceinline__ float bf2f(u16 h) { return __uint_as_float(((unsigned)h) << 16); }
; __device__ __forceinline__ unsigned pack2(float a, float b) { return (unsigned)f2bf(a) | ((unsigned)f2bf(b) << 16); }
; __device__ __forceinline__ void hyena_lat_job(const Params& p, char* smem, int l, int c) {
;     ...
;         int t0 = tb + 32 * mt + 8 * g;
;         float uu[6];
;         {
;           const uint2 mid = *(const uint2*)&u[t0];
;           uu[0] = t0 > 0 ? bf2f(u[t0 - 1]) : 0.f;
;           uu[1] = __uint_as_float(mid.x << 16); uu[2] = __uint_as_float(mid.x & 0xffff0000u);
;           uu[3] = __uint_as_float(mid.y << 16); uu[4] = __uint_as_float(mid.y & 0xffff0000u);
;           uu[5] = t0 + 4 < 8192 ? bf2f(u[t0 + 4]) : 0.f;
;         }
;         const int zi0 = b * 10240 + (t0 >> 5) * 40 + (t0 & 31);
;         const uint2 zo = *(const uint2*)&zs[zi0];
;         float zold4[4] = {__uint_as_float(zo.x << 16), __uint_as_float(zo.x & 0xffff0000u),
;                           __uint_as_float(zo.y << 16), __uint_as_float(zo.y & 0xffff0000u)};
;         float zn4[4];
; #pragma unroll
;         for (int q = 0; q < 4; ++q) {
;           float gate = bb + w0 * uu[q] + w1 * uu[q + 1] + w2 * uu[q + 2];
;           zn4[q] = gate * (scale * acc[mt][g * 4 + q] + zold4[q] * skip);
;         }
;         if (o == 0) {
;           uint2 zw; zw.x = pack2(zn4[0], zn4[1]); zw.y = pack2(zn4[2], zn4[3]);
;           *(uint2*)&zs[zi0] = zw;
;         } else {
; #pragma unroll
;           for (int q = 0; q < 4; ++q) MIX[(size_t)(b * 8192 + t0 + q) * 1024 + 512 + c] = f2bf(zn4[q]);
.LBB0_1121:
	global_load_dwordx2 v[4:5], v[76:77], off offset:208
	s_movk_i32 s0, 0xff98
	v_add_u32_e32 v0, 0x68, v78
	v_cmp_lt_i32_e32 vcc, s0, v78
	v_mov_b32_e32 v244, 0
	v_mov_b32_e32 v245, 0
	s_and_saveexec_b64 s[0:1], vcc
	v_lshl_add_u64 v[18:19], v[0:1], 1, v[80:81]
	v_add_co_u32_e32 v18, vcc, -2, v18
	s_nop 1
	v_addc_co_u32_e32 v19, vcc, -1, v19, vcc
	global_load_ushort v244, v[18:19], off
	s_or_b64 exec, exec, s[0:1]
	s_movk_i32 s0, 0x1f94
	v_cmp_gt_i32_e32 vcc, s0, v78
	s_and_saveexec_b64 s[0:1], vcc
	global_load_ushort v245, v[76:77], off offset:216
	s_or_b64 exec, exec, s[0:1]
	s_waitcnt vmcnt(0) lgkmcnt(0)
	v_lshlrev_b32_e32 v18, 16, v244
	v_lshlrev_b32_e32 v3, 16, v245
	v_ashrrev_i32_e32 v2, 5, v0
	v_mul_lo_u32 v2, v2, s54
	v_add3_u32 v20, v130, v2, v86
	ds_read_b64 v[26:27], v20
	s_waitcnt vmcnt(0) lgkmcnt(0)
	v_and_b32_e32 v24, 0xffff0000, v4
	v_mov_b32_e32 v19, v24
	v_lshlrev_b32_e32 v22, 16, v4
	v_lshlrev_b32_e32 v23, 16, v5
	v_pk_fma_f32 v[18:19], v[70:71], v[18:19], v[74:75]
	v_and_b32_e32 v25, 0xffff0000, v5
	v_mov_b32_e32 v2, v23
	v_lshlrev_b32_e32 v5, 16, v27
	v_lshlrev_b32_e32 v4, 16, v26
	v_and_b32_e32 v27, 0xffff0000, v27
	v_and_b32_e32 v26, 0xffff0000, v26
	v_pk_fma_f32 v[18:19], v[68:69], v[22:23], v[18:19]
	v_pk_fma_f32 v[22:23], v[70:71], v[22:23], v[74:75]
	v_mov_b32_e32 v28, v6
	v_mov_b32_e32 v29, v8
	v_pk_mul_f32 v[4:5], v[66:67], v[4:5]
	v_pk_fma_f32 v[22:23], v[68:69], v[24:25], v[22:23]
	v_mov_b32_e32 v8, v7
	v_pk_mul_f32 v[6:7], v[66:67], v[26:27]
	v_pk_fma_f32 v[18:19], v[72:73], v[24:25], v[18:19]
	v_pk_fma_f32 v[4:5], v[28:29], v[82:83], v[4:5]
	v_pk_fma_f32 v[2:3], v[72:73], v[2:3], v[22:23]
	v_pk_fma_f32 v[6:7], v[8:9], v[82:83], v[6:7]
	v_pk_mul_f32 v[4:5], v[18:19], v[4:5]
	v_pk_mul_f32 v[2:3], v[2:3], v[6:7]
	s_and_b64 vcc, exec, s[50:51]
	s_mov_b64 s[0:1], -1
	s_cbranch_vccnz .LBB0_1127
	v_add_u32_e32 v6, v0, v128
	v_ashrrev_i32_e32 v7, 31, v6
	v_bfe_u32 v0, v4, 16, 1
	v_lshlrev_b64 v[6:7], 11, v[6:7]
	v_add3_u32 v0, v4, v0, s33
	v_lshl_add_u64 v[6:7], s[4:5], 0, v[6:7]
	global_store_short_d16_hi v[6:7], v0, off
	v_bfe_u32 v0, v2, 16, 1
	v_add3_u32 v0, v2, v0, s33
	global_store_short_d16_hi v[6:7], v0, off offset:2048
	v_bfe_u32 v0, v5, 16, 1
	v_add_co_u32_e32 v6, vcc, 0x1000, v6
	v_add3_u32 v0, v5, v0, s33
	s_nop 0
	v_addc_co_u32_e32 v7, vcc, 0, v7, vcc
	global_store_short_d16_hi v[6:7], v0, off
	v_bfe_u32 v0, v3, 16, 1
	v_add3_u32 v0, v3, v0, s33
	s_mov_b64 s[0:1], 0
	global_store_short_d16_hi v[6:7], v0, off offset:2048

; __device__ __forceinline__ float bf2f(u16 h) { return __uint_as_float(((unsigned)h) << 16); }
; __device__ __forceinline__ unsigned pack2(float a, float b) { return (unsigned)f2bf(a) | ((unsigned)f2bf(b) << 16); }
; __device__ __forceinline__ void hyena_lat_job(const Params& p, char* smem, int l, int c) {
;     ...
;         int t0 = tb + 32 * mt + 8 * g;
;         float uu[6];
;         {
;           const uint2 mid = *(const uint2*)&u[t0];
;           uu[0] = t0 > 0 ? bf2f(u[t0 - 1]) : 0.f;
;           uu[1] = __uint_as_float(mid.x << 16); uu[2] = __uint_as_float(mid.x & 0xffff0000u);
;           uu[3] = __uint_as_float(mid.y << 16); uu[4] = __uint_as_float(mid.y & 0xffff0000u);
;           uu[5] = t0 + 4 < 8192 ? bf2f(u[t0 + 4]) : 0.f;
;         }
;         const int zi0 = b * 10240 + (t0 >> 5) * 40 + (t0 & 31);
;         const uint2 zo = *(const uint2*)&zs[zi0];
;         float zold4[4] = {__uint_as_float(zo.x << 16), __uint_as_float(zo.x & 0xffff0000u),
;                           __uint_as_float(zo.y << 16), __uint_as_float(zo.y & 0xffff0000u)};
;         float zn4[4];
; #pragma unroll
;         for (int q = 0; q < 4; ++q) {
;           float gate = bb + w0 * uu[q] + w1 * uu[q + 1] + w2 * uu[q + 2];
;           zn4[q] = gate * (scale * acc[mt][g * 4 + q] + zold4[q] * skip);
;         }
;         if (o == 0) {
;           uint2 zw; zw.x = pack2(zn4[0], zn4[1]); zw.y = pack2(zn4[2], zn4[3]);
;           *(uint2*)&zs[zi0] = zw;
;         } else {
; #pragma unroll
;           for (int q = 0; q < 4; ++q) MIX[(size_t)(b * 8192 + t0 + q) * 1024 + 512 + c] = f2bf(zn4[q]);
.LBB0_1129:
	global_load_dwordx2 v[4:5], v[76:77], off offset:224
	s_movk_i32 s0, 0xff90
	v_add_u32_e32 v0, 0x70, v78
	v_cmp_lt_i32_e32 vcc, s0, v78
	v_mov_b32_e32 v244, 0
	v_mov_b32_e32 v245, 0
	s_and_saveexec_b64 s[0:1], vcc
	v_lshl_add_u64 v[6:7], v[0:1], 1, v[80:81]
	v_add_co_u32_e32 v6, vcc, -2, v6
	s_nop 1
	v_addc_co_u32_e32 v7, vcc, -1, v7, vcc
	global_load_ushort v244, v[6:7], off
	s_or_b64 exec, exec, s[0:1]
	s_movk_i32 s0, 0x1f8c
	v_cmp_gt_i32_e32 vcc, s0, v78
	s_and_saveexec_b64 s[0:1], vcc
	global_load_ushort v245, v[76:77], off offset:232
	s_or_b64 exec, exec, s[0:1]
	s_waitcnt vmcnt(0) lgkmcnt(0)
	v_lshlrev_b32_e32 v6, 16, v244
	v_lshlrev_b32_e32 v3, 16, v245
	v_ashrrev_i32_e32 v2, 5, v0
	v_mul_lo_u32 v2, v2, s54
	v_add3_u32 v8, v130, v2, v56
	ds_read_b64 v[22:23], v8
	s_waitcnt vmcnt(0) lgkmcnt(0)
	v_and_b32_e32 v20, 0xffff0000, v4
	v_mov_b32_e32 v7, v20
	v_lshlrev_b32_e32 v18, 16, v4
	v_lshlrev_b32_e32 v19, 16, v5
	v_pk_fma_f32 v[6:7], v[70:71], v[6:7], v[74:75]
	v_and_b32_e32 v21, 0xffff0000, v5
	v_mov_b32_e32 v2, v19
	v_lshlrev_b32_e32 v5, 16, v23
	v_lshlrev_b32_e32 v4, 16, v22
	v_and_b32_e32 v23, 0xffff0000, v23
	v_and_b32_e32 v22, 0xffff0000, v22
	v_pk_fma_f32 v[6:7], v[68:69], v[18:19], v[6:7]
	v_pk_fma_f32 v[18:19], v[70:71], v[18:19], v[74:75]
	v_mov_b32_e32 v24, v10
	v_mov_b32_e32 v25, v12
	v_pk_mul_f32 v[4:5], v[66:67], v[4:5]
	v_pk_fma_f32 v[18:19], v[68:69], v[20:21], v[18:19]
	v_mov_b32_e32 v12, v11
	v_pk_mul_f32 v[10:11], v[66:67], v[22:23]
	v_pk_fma_f32 v[6:7], v[72:73], v[20:21], v[6:7]
	v_pk_fma_f32 v[4:5], v[24:25], v[82:83], v[4:5]
	v_pk_fma_f32 v[2:3], v[72:73], v[2:3], v[18:19]
	v_pk_fma_f32 v[10:11], v[12:13], v[82:83], v[10:11]
	v_pk_mul_f32 v[4:5], v[6:7], v[4:5]
	v_pk_mul_f32 v[2:3], v[2:3], v[10:11]
	s_and_b64 vcc, exec, s[50:51]
	s_mov_b64 s[0:1], -1
	s_cbranch_vccnz .LBB0_1135
	v_add_u32_e32 v6, v0, v128
	v_ashrrev_i32_e32 v7, 31, v6
	v_bfe_u32 v0, v4, 16, 1
	v_lshlrev_b64 v[6:7], 11, v[6:7]
	v_add3_u32 v0, v4, v0, s33
	v_lshl_add_u64 v[6:7], s[4:5], 0, v[6:7]
	global_store_short_d16_hi v[6:7], v0, off
	v_bfe_u32 v0, v2, 16, 1
	v_add3_u32 v0, v2, v0, s33
	global_store_short_d16_hi v[6:7], v0, off offset:2048
	v_bfe_u32 v0, v5, 16, 1
	v_add_co_u32_e32 v6, vcc, 0x1000, v6
	v_add3_u32 v0, v5, v0, s33
	s_nop 0
	v_addc_co_u32_e32 v7, vcc, 0, v7, vcc
	global_store_short_d16_hi v[6:7], v0, off
	v_bfe_u32 v0, v3, 16, 1
	v_add3_u32 v0, v3, v0, s33
	s_mov_b64 s[0:1], 0
	global_store_short_d16_hi v[6:7], v0, off offset:2048

; __device__ __forceinline__ float bf2f(u16 h) { return __uint_as_float(((unsigned)h) << 16); }
; __device__ __forceinline__ unsigned pack2(float a, float b) { return (unsigned)f2bf(a) | ((unsigned)f2bf(b) << 16); }
; __device__ __forceinline__ void hyena_lat_job(const Params& p, char* smem, int l, int c) {
;     ...
;         int t0 = tb + 32 * mt + 8 * g;
;         float uu[6];
;         {
;           const uint2 mid = *(const uint2*)&u[t0];
;           uu[0] = t0 > 0 ? bf2f(u[t0 - 1]) : 0.f;
;           uu[1] = __uint_as_float(mid.x << 16); uu[2] = __uint_as_float(mid.x & 0xffff0000u);
;           uu[3] = __uint_as_float(mid.y << 16); uu[4] = __uint_as_float(mid.y & 0xffff0000u);
;           uu[5] = t0 + 4 < 8192 ? bf2f(u[t0 + 4]) : 0.f;
;         }
;         const int zi0 = b * 10240 + (t0 >> 5) * 40 + (t0 & 31);
;         const uint2 zo = *(const uint2*)&zs[zi0];
;         float zold4[4] = {__uint_as_float(zo.x << 16), __uint_as_float(zo.x & 0xffff0000u),
;                           __uint_as_float(zo.y << 16), __uint_as_float(zo.y & 0xffff0000u)};
;         float zn4[4];
; #pragma unroll
;         for (int q = 0; q < 4; ++q) {
;           float gate = bb + w0 * uu[q] + w1 * uu[q + 1] + w2 * uu[q + 2];
;           zn4[q] = gate * (scale * acc[mt][g * 4 + q] + zold4[q] * skip);
;         }
;         if (o == 0) {
;           uint2 zw; zw.x = pack2(zn4[0], zn4[1]); zw.y = pack2(zn4[2], zn4[3]);
;           *(uint2*)&zs[zi0] = zw;
;         } else {
; #pragma unroll
;           for (int q = 0; q < 4; ++q) MIX[(size_t)(b * 8192 + t0 + q) * 1024 + 512 + c] = f2bf(zn4[q]);
.LBB0_1137:
	global_load_dwordx2 v[4:5], v[76:77], off offset:240
	s_movk_i32 s0, 0xff88
	v_add_u32_e32 v0, 0x78, v78
	v_cmp_lt_i32_e32 vcc, s0, v78
	v_mov_b32_e32 v244, 0
	v_mov_b32_e32 v245, 0
	s_and_saveexec_b64 s[0:1], vcc
	v_lshl_add_u64 v[6:7], v[0:1], 1, v[80:81]
	v_add_co_u32_e32 v6, vcc, -2, v6
	s_nop 1
	v_addc_co_u32_e32 v7, vcc, -1, v7, vcc
	global_load_ushort v244, v[6:7], off
	s_or_b64 exec, exec, s[0:1]
	s_movk_i32 s0, 0x1f84
	v_cmp_gt_i32_e32 vcc, s0, v78
	s_and_saveexec_b64 s[0:1], vcc
	global_load_ushort v245, v[76:77], off offset:248
	s_or_b64 exec, exec, s[0:1]
	s_waitcnt vmcnt(0) lgkmcnt(0)
	v_lshlrev_b32_e32 v6, 16, v244
	v_lshlrev_b32_e32 v3, 16, v245
	v_ashrrev_i32_e32 v2, 5, v0
	v_mul_lo_u32 v2, v2, s54
	v_add3_u32 v8, v130, v2, v57
	ds_read_b64 v[18:19], v8
	s_waitcnt vmcnt(0) lgkmcnt(0)
	v_and_b32_e32 v12, 0xffff0000, v4
	v_mov_b32_e32 v7, v12
	v_lshlrev_b32_e32 v10, 16, v4
	v_lshlrev_b32_e32 v11, 16, v5
	v_pk_fma_f32 v[6:7], v[70:71], v[6:7], v[74:75]
	v_and_b32_e32 v13, 0xffff0000, v5
	v_mov_b32_e32 v2, v11
	v_pk_fma_f32 v[6:7], v[68:69], v[10:11], v[6:7]
	v_pk_fma_f32 v[10:11], v[70:71], v[10:11], v[74:75]
	v_lshlrev_b32_e32 v5, 16, v19
	v_lshlrev_b32_e32 v4, 16, v18
	v_and_b32_e32 v19, 0xffff0000, v19
	v_and_b32_e32 v18, 0xffff0000, v18
	v_pk_fma_f32 v[10:11], v[68:69], v[12:13], v[10:11]
	v_mov_b32_e32 v20, v14
	v_mov_b32_e32 v21, v16
	v_pk_mul_f32 v[4:5], v[66:67], v[4:5]
	v_pk_fma_f32 v[2:3], v[72:73], v[2:3], v[10:11]
	v_mov_b32_e32 v16, v15
	v_pk_mul_f32 v[10:11], v[66:67], v[18:19]
	v_pk_fma_f32 v[6:7], v[72:73], v[12:13], v[6:7]
	v_pk_fma_f32 v[4:5], v[20:21], v[82:83], v[4:5]
	v_pk_fma_f32 v[10:11], v[16:17], v[82:83], v[10:11]
	v_pk_mul_f32 v[4:5], v[6:7], v[4:5]
	v_pk_mul_f32 v[2:3], v[2:3], v[10:11]
	s_and_b64 vcc, exec, s[50:51]
	s_mov_b64 s[0:1], -1
	s_cbranch_vccnz .LBB0_1143
	v_add_u32_e32 v6, v0, v128
	v_ashrrev_i32_e32 v7, 31, v6
	v_bfe_u32 v0, v4, 16, 1
	v_lshlrev_b64 v[6:7], 11, v[6:7]
	v_add3_u32 v0, v4, v0, s33
	v_lshl_add_u64 v[6:7], s[4:5], 0, v[6:7]
	global_store_short_d16_hi v[6:7], v0, off
	v_bfe_u32 v0, v2, 16, 1
	v_add3_u32 v0, v2, v0, s33
	global_store_short_d16_hi v[6:7], v0, off offset:2048
	v_bfe_u32 v0, v5, 16, 1
	v_add_co_u32_e32 v6, vcc, 0x1000, v6
	v_add3_u32 v0, v5, v0, s33
	s_nop 0
	v_addc_co_u32_e32 v7, vcc, 0, v7, vcc
	global_store_short_d16_hi v[6:7], v0, off
	v_bfe_u32 v0, v3, 16, 1
	v_add3_u32 v0, v3, v0, s33
	global_store_short_d16_hi v[6:7], v0, off offset:2048
	s_cbranch_execnz .LBB0_982
	s_branch .LBB0_1144

; __global__ void __launch_bounds__(256, 2) fwd_megakernel(Params p) {
	.amdhsa_kernel _Z14fwd_megakernel6Params
		.amdhsa_group_segment_fixed_size 65492
		.amdhsa_private_segment_fixed_size 0
		.amdhsa_kernarg_size 496
		.amdhsa_user_sgpr_count 2
		.amdhsa_user_sgpr_dispatch_ptr 0
		.amdhsa_user_sgpr_queue_ptr 0
		.amdhsa_user_sgpr_kernarg_segment_ptr 1
		.amdhsa_user_sgpr_dispatch_id 0
		.amdhsa_user_sgpr_kernarg_preload_length 0
		.amdhsa_user_sgpr_kernarg_preload_offset 0
		.amdhsa_user_sgpr_private_segment_size 0
		.amdhsa_uses_dynamic_stack 0
		.amdhsa_enable_private_segment 0
		.amdhsa_system_sgpr_workgroup_id_x 1
		.amdhsa_system_sgpr_workgroup_id_y 0
		.amdhsa_system_sgpr_workgroup_id_z 0
		.amdhsa_system_sgpr_workgroup_info 0
		.amdhsa_system_vgpr_workitem_id 2
		.amdhsa_next_free_vgpr 256
		.amdhsa_next_free_sgpr 100
		.amdhsa_accum_offset 256
		.amdhsa_reserve_vcc 1
		.amdhsa_float_round_mode_32 0
		.amdhsa_float_round_mode_16_64 0
		.amdhsa_float_denorm_mode_32 3
		.amdhsa_float_denorm_mode_16_64 3
		.amdhsa_dx10_clamp 1
		.amdhsa_ieee_mode 1
		.amdhsa_fp16_overflow 0
		.amdhsa_tg_split 0
		.amdhsa_exception_fp_ieee_invalid_op 0
		.amdhsa_exception_fp_denorm_src 0
		.amdhsa_exception_fp_ieee_div_zero 0
		.amdhsa_exception_fp_ieee_overflow 0
		.amdhsa_exception_fp_ieee_underflow 0
		.amdhsa_exception_fp_ieee_inexact 0
		.amdhsa_exception_int_div_zero 0
	.end_amdhsa_kernel

; __global__ void __launch_bounds__(256, 2) fwd_megakernel(Params p) {
amdhsa.kernels:
  - .agpr_count:     0
    .args:
      - .offset:         0
        .size:           240
        .value_kind:     by_value
      - .offset:         240
        .size:           4
        .value_kind:     hidden_block_count_x
      - .offset:         244
        .size:           4
        .value_kind:     hidden_block_count_y
      - .offset:         248
        .size:           4
        .value_kind:     hidden_block_count_z
      - .offset:         252
        .size:           2
        .value_kind:     hidden_group_size_x
      - .offset:         254
        .size:           2
        .value_kind:     hidden_group_size_y
      - .offset:         256
        .size:           2
        .value_kind:     hidden_group_size_z
      - .offset:         258
        .size:           2
        .value_kind:     hidden_remainder_x
      - .offset:         260
        .size:           2
        .value_kind:     hidden_remainder_y
      - .offset:         262
        .size:           2
        .value_kind:     hidden_remainder_z
      - .offset:         280
        .size:           8
        .value_kind:     hidden_global_offset_x
      - .offset:         288
        .size:           8
        .value_kind:     hidden_global_offset_y
      - .offset:         296
        .size:           8
        .value_kind:     hidden_global_offset_z
      - .offset:         304
        .size:           2
        .value_kind:     hidden_grid_dims
      - .offset:         328
        .size:           8
        .value_kind:     hidden_multigrid_sync_arg
    .group_segment_fixed_size: 65492
    .kernarg_segment_align: 8
    .kernarg_segment_size: 496
    .language:       OpenCL C
    .language_version:
      - 2
      - 0
    .max_flat_workgroup_size: 256
    .name:           _Z14fwd_megakernel6Params
    .private_segment_fixed_size: 0
    .sgpr_count:     106
    .sgpr_spill_count: 238
    .symbol:         _Z14fwd_megakernel6Params.kd
    .uniform_work_group_size: 1
    .uses_dynamic_stack: false
    .vgpr_count:     256
    .vgpr_spill_count: 0
    .wavefront_size: 64
